# ctx-M GEMM copy: same batched hook + epilogue gate loads
# baseline (speedup 1.0000x reference)
; __device__ __forceinline__ float fast_rcp(float x) { return __builtin_amdgcn_rcpf(x); }
;     __device__ __forceinline__ void mid(f32x4 (&acc)[2][2][4][2], const Unit& u, int wr, int wc, int fr, int fq, int t) const {
;         int fr_ = fr; asm volatile("" : "+v"(fr_));
;         const int row0 = u.pm * 256 + wr * 64 + fr_, col0 = u.pn * 256 + wc * 32 + 8 * fq, noff = C_GATE + (t == 8 ? 0 : 2048);
; #pragma unroll
;         for (int ai = 0; ai < 2; ++ai)
; #pragma unroll
;             for (int m = 0; m < 4; ++m) {
;                 const bf16_t* gp = P + (size_t)(row0 + ai * 128 + m * 16) * PS + noff + col0;
; #pragma unroll
;                 for (int bj = 0; bj < 2; ++bj) {
;                     const u32x4 gn = *(const u32x4*)(gp + bj * 128), gd = *(const u32x4*)(gp + bj * 128 + 2048);
;                     f32x4 r0, r1;
;                     r0[0] = bflo(gn.x) * fast_rcp(fmaxf(bflo(gd.x), 1e-20f)); r0[1] = bfhi(gn.x) * fast_rcp(fmaxf(bfhi(gd.x), 1e-20f));
;                     r0[2] = bflo(gn.y) * fast_rcp(fmaxf(bflo(gd.y), 1e-20f)); r0[3] = bfhi(gn.y) * fast_rcp(fmaxf(bfhi(gd.y), 1e-20f));
;                     r1[0] = bflo(gn.z) * fast_rcp(fmaxf(bflo(gd.z), 1e-20f)); r1[1] = bfhi(gn.z) * fast_rcp(fmaxf(bfhi(gd.z), 1e-20f));
;                     r1[2] = bflo(gn.w) * fast_rcp(fmaxf(bflo(gd.w), 1e-20f)); r1[3] = bfhi(gn.w) * fast_rcp(fmaxf(bfhi(gd.w), 1e-20f));
;                     acc[ai][bj][m][0] *= r0; acc[ai][bj][m][1] *= r1;
;                 }
;                 if (m == 1 || m == 3) __builtin_amdgcn_sched_barrier(0);
.LBB0_788:
	s_andn2_b64 vcc, exec, s[6:7]
	s_cbranch_vccnz .LBB0_790
	v_add_u32_e32 v34, s68, v173
	s_cmp_eq_u32 s12, 8
	v_mov_b64_e32 v[36:37], s[40:41]
	s_cselect_b32 s24, s20, 0x4000
	v_mad_i64_i32 v[36:37], vcc, v34, s90, v[36:37]
	s_mov_b32 s5, 0
	v_lshl_add_u64 v[36:37], v[36:37], 0, s[24:25]
	s_movk_i32 s4, 0x800
	v_lshl_add_u64 v[36:37], v[36:37], 0, v[164:165]
	v_lshl_add_u64 v[36:37], v[36:37], 0, s[4:5]
	s_mov_b32 s4, 0x60000
	global_load_dwordx4 v[134:137], v[36:37], off offset:-2048
	global_load_dwordx4 v[138:141], v[36:37], off offset:2048
	global_load_dwordx4 v[178:181], v[36:37], off offset:-1792
	global_load_dwordx4 v[182:185], v[36:37], off offset:2304
	v_lshl_add_u64 v[36:37], v[36:37], 0, s[4:5]
	global_load_dwordx4 v[186:189], v[36:37], off offset:-2048
	global_load_dwordx4 v[190:193], v[36:37], off offset:2048
	global_load_dwordx4 v[194:197], v[36:37], off offset:-1792
	global_load_dwordx4 v[198:201], v[36:37], off offset:2304
	v_lshl_add_u64 v[36:37], v[36:37], 0, s[4:5]
	global_load_dwordx4 v[202:205], v[36:37], off offset:-2048
	global_load_dwordx4 v[206:209], v[36:37], off offset:2048
	global_load_dwordx4 v[210:213], v[36:37], off offset:-1792
	global_load_dwordx4 v[214:217], v[36:37], off offset:2304
	v_lshl_add_u64 v[36:37], v[36:37], 0, s[4:5]
	global_load_dwordx4 v[218:221], v[36:37], off offset:-2048
	global_load_dwordx4 v[222:225], v[36:37], off offset:2048
	global_load_dwordx4 v[226:229], v[36:37], off offset:-1792
	global_load_dwordx4 v[230:233], v[36:37], off offset:2304
	v_lshl_add_u64 v[36:37], v[36:37], 0, s[4:5]
	s_mov_b32 s4, 0x180000
	v_lshl_add_u64 v[36:37], v[36:37], 0, s[4:5]
	s_mov_b32 s4, 0x60000
	s_waitcnt vmcnt(14)
	v_lshlrev_b32_e32 v246, 16, v138
	v_and_b32_e32 v247, 0xffff0000, v138
	v_lshlrev_b32_e32 v248, 16, v139
	v_and_b32_e32 v249, 0xffff0000, v139
	v_max_f32_e32 v246, v246, v246
	v_max_f32_e32 v247, v247, v247
	v_max_f32_e32 v248, v248, v248
	v_max_f32_e32 v249, v249, v249
	v_max_f32_e32 v246, 0x1e3ce508, v246
	v_max_f32_e32 v247, 0x1e3ce508, v247
	v_max_f32_e32 v248, 0x1e3ce508, v248
	v_max_f32_e32 v249, 0x1e3ce508, v249
	v_rcp_f32_e32 v246, v246
	v_rcp_f32_e32 v247, v247
	v_rcp_f32_e32 v248, v248
	v_rcp_f32_e32 v249, v249
	v_lshlrev_b32_e32 v250, 16, v134
	v_and_b32_e32 v251, 0xffff0000, v134
	v_lshlrev_b32_e32 v252, 16, v135
	v_and_b32_e32 v253, 0xffff0000, v135
	v_pk_mul_f32 v[246:247], v[246:247], v[250:251]
	v_pk_mul_f32 v[248:249], v[248:249], v[252:253]
	v_pk_mul_f32 v[130:131], v[130:131], v[246:247]
	v_pk_mul_f32 v[132:133], v[132:133], v[248:249]
	v_lshlrev_b32_e32 v246, 16, v140
	v_and_b32_e32 v247, 0xffff0000, v140
	v_lshlrev_b32_e32 v248, 16, v141
	v_and_b32_e32 v249, 0xffff0000, v141
	v_max_f32_e32 v246, v246, v246
	v_max_f32_e32 v247, v247, v247
	v_max_f32_e32 v248, v248, v248
	v_max_f32_e32 v249, v249, v249
	v_max_f32_e32 v246, 0x1e3ce508, v246
	v_max_f32_e32 v247, 0x1e3ce508, v247
	v_max_f32_e32 v248, 0x1e3ce508, v248
	v_max_f32_e32 v249, 0x1e3ce508, v249
	v_rcp_f32_e32 v246, v246
	v_rcp_f32_e32 v247, v247
	v_rcp_f32_e32 v248, v248
	v_rcp_f32_e32 v249, v249
	v_lshlrev_b32_e32 v250, 16, v136
	v_and_b32_e32 v251, 0xffff0000, v136
	v_lshlrev_b32_e32 v252, 16, v137
	v_and_b32_e32 v253, 0xffff0000, v137
	v_pk_mul_f32 v[246:247], v[246:247], v[250:251]
	v_pk_mul_f32 v[248:249], v[248:249], v[252:253]
	v_pk_mul_f32 v[126:127], v[126:127], v[246:247]
	v_pk_mul_f32 v[128:129], v[128:129], v[248:249]
	global_load_dwordx4 v[134:137], v[36:37], off offset:-2048
	global_load_dwordx4 v[138:141], v[36:37], off offset:2048
	s_waitcnt vmcnt(14)
	v_lshlrev_b32_e32 v246, 16, v182
	v_and_b32_e32 v247, 0xffff0000, v182
	v_lshlrev_b32_e32 v248, 16, v183
	v_and_b32_e32 v249, 0xffff0000, v183
	v_max_f32_e32 v246, v246, v246
	v_max_f32_e32 v247, v247, v247
	v_max_f32_e32 v248, v248, v248
	v_max_f32_e32 v249, v249, v249
	v_max_f32_e32 v246, 0x1e3ce508, v246
	v_max_f32_e32 v247, 0x1e3ce508, v247
	v_max_f32_e32 v248, 0x1e3ce508, v248
	v_max_f32_e32 v249, 0x1e3ce508, v249
	v_rcp_f32_e32 v246, v246
	v_rcp_f32_e32 v247, v247
	v_rcp_f32_e32 v248, v248
	v_rcp_f32_e32 v249, v249
	v_lshlrev_b32_e32 v250, 16, v178
	v_and_b32_e32 v251, 0xffff0000, v178
	v_lshlrev_b32_e32 v252, 16, v179
	v_and_b32_e32 v253, 0xffff0000, v179
	v_pk_mul_f32 v[246:247], v[246:247], v[250:251]
	v_pk_mul_f32 v[248:249], v[248:249], v[252:253]
	v_pk_mul_f32 v[122:123], v[122:123], v[246:247]
	v_pk_mul_f32 v[124:125], v[124:125], v[248:249]
	v_lshlrev_b32_e32 v246, 16, v184
	v_and_b32_e32 v247, 0xffff0000, v184
	v_lshlrev_b32_e32 v248, 16, v185
	v_and_b32_e32 v249, 0xffff0000, v185
	v_max_f32_e32 v246, v246, v246
	v_max_f32_e32 v247, v247, v247
	v_max_f32_e32 v248, v248, v248
	v_max_f32_e32 v249, v249, v249
	v_max_f32_e32 v246, 0x1e3ce508, v246
	v_max_f32_e32 v247, 0x1e3ce508, v247
	v_max_f32_e32 v248, 0x1e3ce508, v248
	v_max_f32_e32 v249, 0x1e3ce508, v249
	v_rcp_f32_e32 v246, v246
	v_rcp_f32_e32 v247, v247
	v_rcp_f32_e32 v248, v248
	v_rcp_f32_e32 v249, v249
	v_lshlrev_b32_e32 v250, 16, v180
	v_and_b32_e32 v251, 0xffff0000, v180
	v_lshlrev_b32_e32 v252, 16, v181
	v_and_b32_e32 v253, 0xffff0000, v181
	v_pk_mul_f32 v[246:247], v[246:247], v[250:251]
	v_pk_mul_f32 v[248:249], v[248:249], v[252:253]
	v_pk_mul_f32 v[118:119], v[118:119], v[246:247]
	v_pk_mul_f32 v[120:121], v[120:121], v[248:249]
	global_load_dwordx4 v[178:181], v[36:37], off offset:-1792
	global_load_dwordx4 v[182:185], v[36:37], off offset:2304
	v_lshl_add_u64 v[36:37], v[36:37], 0, s[4:5]
	s_waitcnt vmcnt(14)
; __device__ __forceinline__ float fast_rcp(float x) { return __builtin_amdgcn_rcpf(x); }
;     __device__ __forceinline__ void mid(f32x4 (&acc)[2][2][4][2], const Unit& u, int wr, int wc, int fr, int fq, int t) const {
;     ...
;                     const u32x4 gn = *(const u32x4*)(gp + bj * 128), gd = *(const u32x4*)(gp + bj * 128 + 2048);
;                     f32x4 r0, r1;
;                     r0[0] = bflo(gn.x) * fast_rcp(fmaxf(bflo(gd.x), 1e-20f)); r0[1] = bfhi(gn.x) * fast_rcp(fmaxf(bfhi(gd.x), 1e-20f));
;                     r0[2] = bflo(gn.y) * fast_rcp(fmaxf(bflo(gd.y), 1e-20f)); r0[3] = bfhi(gn.y) * fast_rcp(fmaxf(bfhi(gd.y), 1e-20f));
;                     r1[0] = bflo(gn.z) * fast_rcp(fmaxf(bflo(gd.z), 1e-20f)); r1[1] = bfhi(gn.z) * fast_rcp(fmaxf(bfhi(gd.z), 1e-20f));
;                     r1[2] = bflo(gn.w) * fast_rcp(fmaxf(bflo(gd.w), 1e-20f)); r1[3] = bfhi(gn.w) * fast_rcp(fmaxf(bfhi(gd.w), 1e-20f));
;                     acc[ai][bj][m][0] *= r0; acc[ai][bj][m][1] *= r1;
;                 }
;                 if (m == 1 || m == 3) __builtin_amdgcn_sched_barrier(0);
	v_lshlrev_b32_e32 v246, 16, v190
	v_and_b32_e32 v247, 0xffff0000, v190
	v_lshlrev_b32_e32 v248, 16, v191
	v_and_b32_e32 v249, 0xffff0000, v191
	v_max_f32_e32 v246, v246, v246
	v_max_f32_e32 v247, v247, v247
	v_max_f32_e32 v248, v248, v248
	v_max_f32_e32 v249, v249, v249
	v_max_f32_e32 v246, 0x1e3ce508, v246
	v_max_f32_e32 v247, 0x1e3ce508, v247
	v_max_f32_e32 v248, 0x1e3ce508, v248
	v_max_f32_e32 v249, 0x1e3ce508, v249
	v_rcp_f32_e32 v246, v246
	v_rcp_f32_e32 v247, v247
	v_rcp_f32_e32 v248, v248
	v_rcp_f32_e32 v249, v249
	v_lshlrev_b32_e32 v250, 16, v186
	v_and_b32_e32 v251, 0xffff0000, v186
	v_lshlrev_b32_e32 v252, 16, v187
	v_and_b32_e32 v253, 0xffff0000, v187
	v_pk_mul_f32 v[246:247], v[246:247], v[250:251]
	v_pk_mul_f32 v[248:249], v[248:249], v[252:253]
	v_pk_mul_f32 v[114:115], v[114:115], v[246:247]
	v_pk_mul_f32 v[116:117], v[116:117], v[248:249]
	v_lshlrev_b32_e32 v246, 16, v192
	v_and_b32_e32 v247, 0xffff0000, v192
	v_lshlrev_b32_e32 v248, 16, v193
	v_and_b32_e32 v249, 0xffff0000, v193
	v_max_f32_e32 v246, v246, v246
	v_max_f32_e32 v247, v247, v247
	v_max_f32_e32 v248, v248, v248
	v_max_f32_e32 v249, v249, v249
	v_max_f32_e32 v246, 0x1e3ce508, v246
	v_max_f32_e32 v247, 0x1e3ce508, v247
	v_max_f32_e32 v248, 0x1e3ce508, v248
	v_max_f32_e32 v249, 0x1e3ce508, v249
	v_rcp_f32_e32 v246, v246
	v_rcp_f32_e32 v247, v247
	v_rcp_f32_e32 v248, v248
	v_rcp_f32_e32 v249, v249
	v_lshlrev_b32_e32 v250, 16, v188
	v_and_b32_e32 v251, 0xffff0000, v188
	v_lshlrev_b32_e32 v252, 16, v189
	v_and_b32_e32 v253, 0xffff0000, v189
	v_pk_mul_f32 v[246:247], v[246:247], v[250:251]
	v_pk_mul_f32 v[248:249], v[248:249], v[252:253]
	v_pk_mul_f32 v[110:111], v[110:111], v[246:247]
	v_pk_mul_f32 v[112:113], v[112:113], v[248:249]
	global_load_dwordx4 v[186:189], v[36:37], off offset:-2048
	global_load_dwordx4 v[190:193], v[36:37], off offset:2048
	s_waitcnt vmcnt(14)
	v_lshlrev_b32_e32 v246, 16, v198
	v_and_b32_e32 v247, 0xffff0000, v198
	v_lshlrev_b32_e32 v248, 16, v199
	v_and_b32_e32 v249, 0xffff0000, v199
	v_max_f32_e32 v246, v246, v246
	v_max_f32_e32 v247, v247, v247
	v_max_f32_e32 v248, v248, v248
	v_max_f32_e32 v249, v249, v249
	v_max_f32_e32 v246, 0x1e3ce508, v246
	v_max_f32_e32 v247, 0x1e3ce508, v247
	v_max_f32_e32 v248, 0x1e3ce508, v248
	v_max_f32_e32 v249, 0x1e3ce508, v249
	v_rcp_f32_e32 v246, v246
	v_rcp_f32_e32 v247, v247
	v_rcp_f32_e32 v248, v248
	v_rcp_f32_e32 v249, v249
	v_lshlrev_b32_e32 v250, 16, v194
	v_and_b32_e32 v251, 0xffff0000, v194
	v_lshlrev_b32_e32 v252, 16, v195
	v_and_b32_e32 v253, 0xffff0000, v195
	v_pk_mul_f32 v[246:247], v[246:247], v[250:251]
	v_pk_mul_f32 v[248:249], v[248:249], v[252:253]
	v_pk_mul_f32 v[106:107], v[106:107], v[246:247]
	v_pk_mul_f32 v[108:109], v[108:109], v[248:249]
	v_lshlrev_b32_e32 v246, 16, v200
	v_and_b32_e32 v247, 0xffff0000, v200
	v_lshlrev_b32_e32 v248, 16, v201
	v_and_b32_e32 v249, 0xffff0000, v201
	v_max_f32_e32 v246, v246, v246
	v_max_f32_e32 v247, v247, v247
	v_max_f32_e32 v248, v248, v248
	v_max_f32_e32 v249, v249, v249
	v_max_f32_e32 v246, 0x1e3ce508, v246
	v_max_f32_e32 v247, 0x1e3ce508, v247
	v_max_f32_e32 v248, 0x1e3ce508, v248
	v_max_f32_e32 v249, 0x1e3ce508, v249
	v_rcp_f32_e32 v246, v246
	v_rcp_f32_e32 v247, v247
	v_rcp_f32_e32 v248, v248
	v_rcp_f32_e32 v249, v249
	v_lshlrev_b32_e32 v250, 16, v196
	v_and_b32_e32 v251, 0xffff0000, v196
	v_lshlrev_b32_e32 v252, 16, v197
	v_and_b32_e32 v253, 0xffff0000, v197
	v_pk_mul_f32 v[246:247], v[246:247], v[250:251]
	v_pk_mul_f32 v[248:249], v[248:249], v[252:253]
	v_pk_mul_f32 v[102:103], v[102:103], v[246:247]
	v_pk_mul_f32 v[104:105], v[104:105], v[248:249]
	global_load_dwordx4 v[194:197], v[36:37], off offset:-1792
	global_load_dwordx4 v[198:201], v[36:37], off offset:2304
	v_lshl_add_u64 v[36:37], v[36:37], 0, s[4:5]
	s_waitcnt vmcnt(14)
	v_lshlrev_b32_e32 v246, 16, v206
	v_and_b32_e32 v247, 0xffff0000, v206
	v_lshlrev_b32_e32 v248, 16, v207
	v_and_b32_e32 v249, 0xffff0000, v207
	v_max_f32_e32 v246, v246, v246
	v_max_f32_e32 v247, v247, v247
	v_max_f32_e32 v248, v248, v248
	v_max_f32_e32 v249, v249, v249
	v_max_f32_e32 v246, 0x1e3ce508, v246
	v_max_f32_e32 v247, 0x1e3ce508, v247
	v_max_f32_e32 v248, 0x1e3ce508, v248
	v_max_f32_e32 v249, 0x1e3ce508, v249
	v_rcp_f32_e32 v246, v246
	v_rcp_f32_e32 v247, v247
	v_rcp_f32_e32 v248, v248
	v_rcp_f32_e32 v249, v249
	v_lshlrev_b32_e32 v250, 16, v202
	v_and_b32_e32 v251, 0xffff0000, v202
	v_lshlrev_b32_e32 v252, 16, v203
	v_and_b32_e32 v253, 0xffff0000, v203
	v_pk_mul_f32 v[246:247], v[246:247], v[250:251]
	v_pk_mul_f32 v[248:249], v[248:249], v[252:253]
	v_pk_mul_f32 v[98:99], v[98:99], v[246:247]
	v_pk_mul_f32 v[100:101], v[100:101], v[248:249]
	v_lshlrev_b32_e32 v246, 16, v208
	v_and_b32_e32 v247, 0xffff0000, v208
	v_lshlrev_b32_e32 v248, 16, v209
	v_and_b32_e32 v249, 0xffff0000, v209
	v_max_f32_e32 v246, v246, v246
	v_max_f32_e32 v247, v247, v247
	v_max_f32_e32 v248, v248, v248
	v_max_f32_e32 v249, v249, v249
	v_max_f32_e32 v246, 0x1e3ce508, v246
	v_max_f32_e32 v247, 0x1e3ce508, v247
	v_max_f32_e32 v248, 0x1e3ce508, v248
	v_max_f32_e32 v249, 0x1e3ce508, v249
	v_rcp_f32_e32 v246, v246
	v_rcp_f32_e32 v247, v247
	v_rcp_f32_e32 v248, v248
	v_rcp_f32_e32 v249, v249
	v_lshlrev_b32_e32 v250, 16, v204
	v_and_b32_e32 v251, 0xffff0000, v204
	v_lshlrev_b32_e32 v252, 16, v205
	v_and_b32_e32 v253, 0xffff0000, v205
	v_pk_mul_f32 v[246:247], v[246:247], v[250:251]
	v_pk_mul_f32 v[248:249], v[248:249], v[252:253]
	v_pk_mul_f32 v[94:95], v[94:95], v[246:247]
	v_pk_mul_f32 v[96:97], v[96:97], v[248:249]
	global_load_dwordx4 v[202:205], v[36:37], off offset:-2048
	global_load_dwordx4 v[206:209], v[36:37], off offset:2048
	s_waitcnt vmcnt(14)
; __device__ __forceinline__ float fast_rcp(float x) { return __builtin_amdgcn_rcpf(x); }
;     __device__ __forceinline__ void mid(f32x4 (&acc)[2][2][4][2], const Unit& u, int wr, int wc, int fr, int fq, int t) const {
;     ...
;                     const u32x4 gn = *(const u32x4*)(gp + bj * 128), gd = *(const u32x4*)(gp + bj * 128 + 2048);
;                     f32x4 r0, r1;
;                     r0[0] = bflo(gn.x) * fast_rcp(fmaxf(bflo(gd.x), 1e-20f)); r0[1] = bfhi(gn.x) * fast_rcp(fmaxf(bfhi(gd.x), 1e-20f));
;                     r0[2] = bflo(gn.y) * fast_rcp(fmaxf(bflo(gd.y), 1e-20f)); r0[3] = bfhi(gn.y) * fast_rcp(fmaxf(bfhi(gd.y), 1e-20f));
;                     r1[0] = bflo(gn.z) * fast_rcp(fmaxf(bflo(gd.z), 1e-20f)); r1[1] = bfhi(gn.z) * fast_rcp(fmaxf(bfhi(gd.z), 1e-20f));
;                     r1[2] = bflo(gn.w) * fast_rcp(fmaxf(bflo(gd.w), 1e-20f)); r1[3] = bfhi(gn.w) * fast_rcp(fmaxf(bfhi(gd.w), 1e-20f));
;                     acc[ai][bj][m][0] *= r0; acc[ai][bj][m][1] *= r1;
;                 }
;                 if (m == 1 || m == 3) __builtin_amdgcn_sched_barrier(0);
	v_lshlrev_b32_e32 v246, 16, v214
	v_and_b32_e32 v247, 0xffff0000, v214
	v_lshlrev_b32_e32 v248, 16, v215
	v_and_b32_e32 v249, 0xffff0000, v215
	v_max_f32_e32 v246, v246, v246
	v_max_f32_e32 v247, v247, v247
	v_max_f32_e32 v248, v248, v248
	v_max_f32_e32 v249, v249, v249
	v_max_f32_e32 v246, 0x1e3ce508, v246
	v_max_f32_e32 v247, 0x1e3ce508, v247
	v_max_f32_e32 v248, 0x1e3ce508, v248
	v_max_f32_e32 v249, 0x1e3ce508, v249
	v_rcp_f32_e32 v246, v246
	v_rcp_f32_e32 v247, v247
	v_rcp_f32_e32 v248, v248
	v_rcp_f32_e32 v249, v249
	v_lshlrev_b32_e32 v250, 16, v210
	v_and_b32_e32 v251, 0xffff0000, v210
	v_lshlrev_b32_e32 v252, 16, v211
	v_and_b32_e32 v253, 0xffff0000, v211
	v_pk_mul_f32 v[246:247], v[246:247], v[250:251]
	v_pk_mul_f32 v[248:249], v[248:249], v[252:253]
	v_pk_mul_f32 v[90:91], v[90:91], v[246:247]
	v_pk_mul_f32 v[92:93], v[92:93], v[248:249]
	v_lshlrev_b32_e32 v246, 16, v216
	v_and_b32_e32 v247, 0xffff0000, v216
	v_lshlrev_b32_e32 v248, 16, v217
	v_and_b32_e32 v249, 0xffff0000, v217
	v_max_f32_e32 v246, v246, v246
	v_max_f32_e32 v247, v247, v247
	v_max_f32_e32 v248, v248, v248
	v_max_f32_e32 v249, v249, v249
	v_max_f32_e32 v246, 0x1e3ce508, v246
	v_max_f32_e32 v247, 0x1e3ce508, v247
	v_max_f32_e32 v248, 0x1e3ce508, v248
	v_max_f32_e32 v249, 0x1e3ce508, v249
	v_rcp_f32_e32 v246, v246
	v_rcp_f32_e32 v247, v247
	v_rcp_f32_e32 v248, v248
	v_rcp_f32_e32 v249, v249
	v_lshlrev_b32_e32 v250, 16, v212
	v_and_b32_e32 v251, 0xffff0000, v212
	v_lshlrev_b32_e32 v252, 16, v213
	v_and_b32_e32 v253, 0xffff0000, v213
	v_pk_mul_f32 v[246:247], v[246:247], v[250:251]
	v_pk_mul_f32 v[248:249], v[248:249], v[252:253]
	v_pk_mul_f32 v[86:87], v[86:87], v[246:247]
	v_pk_mul_f32 v[88:89], v[88:89], v[248:249]
	global_load_dwordx4 v[210:213], v[36:37], off offset:-1792
	global_load_dwordx4 v[214:217], v[36:37], off offset:2304
	v_lshl_add_u64 v[36:37], v[36:37], 0, s[4:5]
	s_waitcnt vmcnt(14)
	v_lshlrev_b32_e32 v246, 16, v222
	v_and_b32_e32 v247, 0xffff0000, v222
	v_lshlrev_b32_e32 v248, 16, v223
	v_and_b32_e32 v249, 0xffff0000, v223
	v_max_f32_e32 v246, v246, v246
	v_max_f32_e32 v247, v247, v247
	v_max_f32_e32 v248, v248, v248
	v_max_f32_e32 v249, v249, v249
	v_max_f32_e32 v246, 0x1e3ce508, v246
	v_max_f32_e32 v247, 0x1e3ce508, v247
	v_max_f32_e32 v248, 0x1e3ce508, v248
	v_max_f32_e32 v249, 0x1e3ce508, v249
	v_rcp_f32_e32 v246, v246
	v_rcp_f32_e32 v247, v247
	v_rcp_f32_e32 v248, v248
	v_rcp_f32_e32 v249, v249
	v_lshlrev_b32_e32 v250, 16, v218
	v_and_b32_e32 v251, 0xffff0000, v218
	v_lshlrev_b32_e32 v252, 16, v219
	v_and_b32_e32 v253, 0xffff0000, v219
	v_pk_mul_f32 v[246:247], v[246:247], v[250:251]
	v_pk_mul_f32 v[248:249], v[248:249], v[252:253]
	v_pk_mul_f32 v[82:83], v[82:83], v[246:247]
	v_pk_mul_f32 v[84:85], v[84:85], v[248:249]
	v_lshlrev_b32_e32 v246, 16, v224
	v_and_b32_e32 v247, 0xffff0000, v224
	v_lshlrev_b32_e32 v248, 16, v225
	v_and_b32_e32 v249, 0xffff0000, v225
	v_max_f32_e32 v246, v246, v246
	v_max_f32_e32 v247, v247, v247
	v_max_f32_e32 v248, v248, v248
	v_max_f32_e32 v249, v249, v249
	v_max_f32_e32 v246, 0x1e3ce508, v246
	v_max_f32_e32 v247, 0x1e3ce508, v247
	v_max_f32_e32 v248, 0x1e3ce508, v248
	v_max_f32_e32 v249, 0x1e3ce508, v249
	v_rcp_f32_e32 v246, v246
	v_rcp_f32_e32 v247, v247
	v_rcp_f32_e32 v248, v248
	v_rcp_f32_e32 v249, v249
	v_lshlrev_b32_e32 v250, 16, v220
	v_and_b32_e32 v251, 0xffff0000, v220
	v_lshlrev_b32_e32 v252, 16, v221
	v_and_b32_e32 v253, 0xffff0000, v221
	v_pk_mul_f32 v[246:247], v[246:247], v[250:251]
	v_pk_mul_f32 v[248:249], v[248:249], v[252:253]
	v_pk_mul_f32 v[78:79], v[78:79], v[246:247]
	v_pk_mul_f32 v[80:81], v[80:81], v[248:249]
	global_load_dwordx4 v[218:221], v[36:37], off offset:-2048
	global_load_dwordx4 v[222:225], v[36:37], off offset:2048
	s_waitcnt vmcnt(14)
	v_lshlrev_b32_e32 v246, 16, v230
	v_and_b32_e32 v247, 0xffff0000, v230
	v_lshlrev_b32_e32 v248, 16, v231
	v_and_b32_e32 v249, 0xffff0000, v231
	v_max_f32_e32 v246, v246, v246
	v_max_f32_e32 v247, v247, v247
	v_max_f32_e32 v248, v248, v248
	v_max_f32_e32 v249, v249, v249
	v_max_f32_e32 v246, 0x1e3ce508, v246
	v_max_f32_e32 v247, 0x1e3ce508, v247
	v_max_f32_e32 v248, 0x1e3ce508, v248
	v_max_f32_e32 v249, 0x1e3ce508, v249
	v_rcp_f32_e32 v246, v246
	v_rcp_f32_e32 v247, v247
	v_rcp_f32_e32 v248, v248
	v_rcp_f32_e32 v249, v249
	v_lshlrev_b32_e32 v250, 16, v226
	v_and_b32_e32 v251, 0xffff0000, v226
	v_lshlrev_b32_e32 v252, 16, v227
	v_and_b32_e32 v253, 0xffff0000, v227
	v_pk_mul_f32 v[246:247], v[246:247], v[250:251]
	v_pk_mul_f32 v[248:249], v[248:249], v[252:253]
	v_pk_mul_f32 v[74:75], v[74:75], v[246:247]
	v_pk_mul_f32 v[76:77], v[76:77], v[248:249]
	v_lshlrev_b32_e32 v246, 16, v232
	v_and_b32_e32 v247, 0xffff0000, v232
	v_lshlrev_b32_e32 v248, 16, v233
	v_and_b32_e32 v249, 0xffff0000, v233
	v_max_f32_e32 v246, v246, v246
	v_max_f32_e32 v247, v247, v247
	v_max_f32_e32 v248, v248, v248
	v_max_f32_e32 v249, v249, v249
	v_max_f32_e32 v246, 0x1e3ce508, v246
	v_max_f32_e32 v247, 0x1e3ce508, v247
	v_max_f32_e32 v248, 0x1e3ce508, v248
	v_max_f32_e32 v249, 0x1e3ce508, v249
	v_rcp_f32_e32 v246, v246
	v_rcp_f32_e32 v247, v247
	v_rcp_f32_e32 v248, v248
	v_rcp_f32_e32 v249, v249
	v_lshlrev_b32_e32 v250, 16, v228
	v_and_b32_e32 v251, 0xffff0000, v228
	v_lshlrev_b32_e32 v252, 16, v229
	v_and_b32_e32 v253, 0xffff0000, v229
	v_pk_mul_f32 v[246:247], v[246:247], v[250:251]
	v_pk_mul_f32 v[248:249], v[248:249], v[252:253]
	v_pk_mul_f32 v[70:71], v[70:71], v[246:247]
	v_pk_mul_f32 v[72:73], v[72:73], v[248:249]
	global_load_dwordx4 v[226:229], v[36:37], off offset:-1792
	global_load_dwordx4 v[230:233], v[36:37], off offset:2304
	v_lshl_add_u64 v[36:37], v[36:37], 0, s[4:5]
	s_waitcnt vmcnt(14)
; __device__ __forceinline__ float fast_rcp(float x) { return __builtin_amdgcn_rcpf(x); }
;     __device__ __forceinline__ void mid(f32x4 (&acc)[2][2][4][2], const Unit& u, int wr, int wc, int fr, int fq, int t) const {
;     ...
;                     const u32x4 gn = *(const u32x4*)(gp + bj * 128), gd = *(const u32x4*)(gp + bj * 128 + 2048);
;                     f32x4 r0, r1;
;                     r0[0] = bflo(gn.x) * fast_rcp(fmaxf(bflo(gd.x), 1e-20f)); r0[1] = bfhi(gn.x) * fast_rcp(fmaxf(bfhi(gd.x), 1e-20f));
;                     r0[2] = bflo(gn.y) * fast_rcp(fmaxf(bflo(gd.y), 1e-20f)); r0[3] = bfhi(gn.y) * fast_rcp(fmaxf(bfhi(gd.y), 1e-20f));
;                     r1[0] = bflo(gn.z) * fast_rcp(fmaxf(bflo(gd.z), 1e-20f)); r1[1] = bfhi(gn.z) * fast_rcp(fmaxf(bfhi(gd.z), 1e-20f));
;                     r1[2] = bflo(gn.w) * fast_rcp(fmaxf(bflo(gd.w), 1e-20f)); r1[3] = bfhi(gn.w) * fast_rcp(fmaxf(bfhi(gd.w), 1e-20f));
;                     acc[ai][bj][m][0] *= r0; acc[ai][bj][m][1] *= r1;
;                 }
;                 if (m == 1 || m == 3) __builtin_amdgcn_sched_barrier(0);
	v_lshlrev_b32_e32 v246, 16, v138
	v_and_b32_e32 v247, 0xffff0000, v138
	v_lshlrev_b32_e32 v248, 16, v139
	v_and_b32_e32 v249, 0xffff0000, v139
	v_max_f32_e32 v246, v246, v246
	v_max_f32_e32 v247, v247, v247
	v_max_f32_e32 v248, v248, v248
	v_max_f32_e32 v249, v249, v249
	v_max_f32_e32 v246, 0x1e3ce508, v246
	v_max_f32_e32 v247, 0x1e3ce508, v247
	v_max_f32_e32 v248, 0x1e3ce508, v248
	v_max_f32_e32 v249, 0x1e3ce508, v249
	v_rcp_f32_e32 v246, v246
	v_rcp_f32_e32 v247, v247
	v_rcp_f32_e32 v248, v248
	v_rcp_f32_e32 v249, v249
	v_lshlrev_b32_e32 v250, 16, v134
	v_and_b32_e32 v251, 0xffff0000, v134
	v_lshlrev_b32_e32 v252, 16, v135
	v_and_b32_e32 v253, 0xffff0000, v135
	v_pk_mul_f32 v[246:247], v[246:247], v[250:251]
	v_pk_mul_f32 v[248:249], v[248:249], v[252:253]
	v_pk_mul_f32 v[66:67], v[66:67], v[246:247]
	v_pk_mul_f32 v[68:69], v[68:69], v[248:249]
	v_lshlrev_b32_e32 v246, 16, v140
	v_and_b32_e32 v247, 0xffff0000, v140
	v_lshlrev_b32_e32 v248, 16, v141
	v_and_b32_e32 v249, 0xffff0000, v141
	v_max_f32_e32 v246, v246, v246
	v_max_f32_e32 v247, v247, v247
	v_max_f32_e32 v248, v248, v248
	v_max_f32_e32 v249, v249, v249
	v_max_f32_e32 v246, 0x1e3ce508, v246
	v_max_f32_e32 v247, 0x1e3ce508, v247
	v_max_f32_e32 v248, 0x1e3ce508, v248
	v_max_f32_e32 v249, 0x1e3ce508, v249
	v_rcp_f32_e32 v246, v246
	v_rcp_f32_e32 v247, v247
	v_rcp_f32_e32 v248, v248
	v_rcp_f32_e32 v249, v249
	v_lshlrev_b32_e32 v250, 16, v136
	v_and_b32_e32 v251, 0xffff0000, v136
	v_lshlrev_b32_e32 v252, 16, v137
	v_and_b32_e32 v253, 0xffff0000, v137
	v_pk_mul_f32 v[246:247], v[246:247], v[250:251]
	v_pk_mul_f32 v[248:249], v[248:249], v[252:253]
	v_pk_mul_f32 v[62:63], v[62:63], v[246:247]
	v_pk_mul_f32 v[64:65], v[64:65], v[248:249]
	s_waitcnt vmcnt(12)
	v_lshlrev_b32_e32 v246, 16, v182
	v_and_b32_e32 v247, 0xffff0000, v182
	v_lshlrev_b32_e32 v248, 16, v183
	v_and_b32_e32 v249, 0xffff0000, v183
	v_max_f32_e32 v246, v246, v246
	v_max_f32_e32 v247, v247, v247
	v_max_f32_e32 v248, v248, v248
	v_max_f32_e32 v249, v249, v249
	v_max_f32_e32 v246, 0x1e3ce508, v246
	v_max_f32_e32 v247, 0x1e3ce508, v247
	v_max_f32_e32 v248, 0x1e3ce508, v248
	v_max_f32_e32 v249, 0x1e3ce508, v249
	v_rcp_f32_e32 v246, v246
	v_rcp_f32_e32 v247, v247
	v_rcp_f32_e32 v248, v248
	v_rcp_f32_e32 v249, v249
	v_lshlrev_b32_e32 v250, 16, v178
	v_and_b32_e32 v251, 0xffff0000, v178
	v_lshlrev_b32_e32 v252, 16, v179
	v_and_b32_e32 v253, 0xffff0000, v179
	v_pk_mul_f32 v[246:247], v[246:247], v[250:251]
	v_pk_mul_f32 v[248:249], v[248:249], v[252:253]
	v_pk_mul_f32 v[58:59], v[58:59], v[246:247]
	v_pk_mul_f32 v[60:61], v[60:61], v[248:249]
	v_lshlrev_b32_e32 v246, 16, v184
	v_and_b32_e32 v247, 0xffff0000, v184
	v_lshlrev_b32_e32 v248, 16, v185
	v_and_b32_e32 v249, 0xffff0000, v185
	v_max_f32_e32 v246, v246, v246
	v_max_f32_e32 v247, v247, v247
	v_max_f32_e32 v248, v248, v248
	v_max_f32_e32 v249, v249, v249
	v_max_f32_e32 v246, 0x1e3ce508, v246
	v_max_f32_e32 v247, 0x1e3ce508, v247
	v_max_f32_e32 v248, 0x1e3ce508, v248
	v_max_f32_e32 v249, 0x1e3ce508, v249
	v_rcp_f32_e32 v246, v246
	v_rcp_f32_e32 v247, v247
	v_rcp_f32_e32 v248, v248
	v_rcp_f32_e32 v249, v249
	v_lshlrev_b32_e32 v250, 16, v180
	v_and_b32_e32 v251, 0xffff0000, v180
	v_lshlrev_b32_e32 v252, 16, v181
	v_and_b32_e32 v253, 0xffff0000, v181
	v_pk_mul_f32 v[246:247], v[246:247], v[250:251]
	v_pk_mul_f32 v[248:249], v[248:249], v[252:253]
	v_pk_mul_f32 v[54:55], v[54:55], v[246:247]
	v_pk_mul_f32 v[56:57], v[56:57], v[248:249]
	s_waitcnt vmcnt(10)
	v_lshlrev_b32_e32 v246, 16, v190
	v_and_b32_e32 v247, 0xffff0000, v190
	v_lshlrev_b32_e32 v248, 16, v191
	v_and_b32_e32 v249, 0xffff0000, v191
	v_max_f32_e32 v246, v246, v246
	v_max_f32_e32 v247, v247, v247
	v_max_f32_e32 v248, v248, v248
	v_max_f32_e32 v249, v249, v249
	v_max_f32_e32 v246, 0x1e3ce508, v246
	v_max_f32_e32 v247, 0x1e3ce508, v247
	v_max_f32_e32 v248, 0x1e3ce508, v248
	v_max_f32_e32 v249, 0x1e3ce508, v249
	v_rcp_f32_e32 v246, v246
	v_rcp_f32_e32 v247, v247
	v_rcp_f32_e32 v248, v248
	v_rcp_f32_e32 v249, v249
	v_lshlrev_b32_e32 v250, 16, v186
	v_and_b32_e32 v251, 0xffff0000, v186
	v_lshlrev_b32_e32 v252, 16, v187
	v_and_b32_e32 v253, 0xffff0000, v187
	v_pk_mul_f32 v[246:247], v[246:247], v[250:251]
	v_pk_mul_f32 v[248:249], v[248:249], v[252:253]
	v_pk_mul_f32 v[50:51], v[50:51], v[246:247]
	v_pk_mul_f32 v[52:53], v[52:53], v[248:249]
	v_lshlrev_b32_e32 v246, 16, v192
	v_and_b32_e32 v247, 0xffff0000, v192
	v_lshlrev_b32_e32 v248, 16, v193
	v_and_b32_e32 v249, 0xffff0000, v193
	v_max_f32_e32 v246, v246, v246
	v_max_f32_e32 v247, v247, v247
	v_max_f32_e32 v248, v248, v248
	v_max_f32_e32 v249, v249, v249
	v_max_f32_e32 v246, 0x1e3ce508, v246
	v_max_f32_e32 v247, 0x1e3ce508, v247
	v_max_f32_e32 v248, 0x1e3ce508, v248
	v_max_f32_e32 v249, 0x1e3ce508, v249
	v_rcp_f32_e32 v246, v246
	v_rcp_f32_e32 v247, v247
	v_rcp_f32_e32 v248, v248
	v_rcp_f32_e32 v249, v249
	v_lshlrev_b32_e32 v250, 16, v188
	v_and_b32_e32 v251, 0xffff0000, v188
	v_lshlrev_b32_e32 v252, 16, v189
	v_and_b32_e32 v253, 0xffff0000, v189
	v_pk_mul_f32 v[246:247], v[246:247], v[250:251]
	v_pk_mul_f32 v[248:249], v[248:249], v[252:253]
	v_pk_mul_f32 v[46:47], v[46:47], v[246:247]
	v_pk_mul_f32 v[48:49], v[48:49], v[248:249]
	s_waitcnt vmcnt(8)
; __device__ __forceinline__ float fast_rcp(float x) { return __builtin_amdgcn_rcpf(x); }
;     __device__ __forceinline__ void mid(f32x4 (&acc)[2][2][4][2], const Unit& u, int wr, int wc, int fr, int fq, int t) const {
;     ...
;                     const u32x4 gn = *(const u32x4*)(gp + bj * 128), gd = *(const u32x4*)(gp + bj * 128 + 2048);
;                     f32x4 r0, r1;
;                     r0[0] = bflo(gn.x) * fast_rcp(fmaxf(bflo(gd.x), 1e-20f)); r0[1] = bfhi(gn.x) * fast_rcp(fmaxf(bfhi(gd.x), 1e-20f));
;                     r0[2] = bflo(gn.y) * fast_rcp(fmaxf(bflo(gd.y), 1e-20f)); r0[3] = bfhi(gn.y) * fast_rcp(fmaxf(bfhi(gd.y), 1e-20f));
;                     r1[0] = bflo(gn.z) * fast_rcp(fmaxf(bflo(gd.z), 1e-20f)); r1[1] = bfhi(gn.z) * fast_rcp(fmaxf(bfhi(gd.z), 1e-20f));
;                     r1[2] = bflo(gn.w) * fast_rcp(fmaxf(bflo(gd.w), 1e-20f)); r1[3] = bfhi(gn.w) * fast_rcp(fmaxf(bfhi(gd.w), 1e-20f));
;                     acc[ai][bj][m][0] *= r0; acc[ai][bj][m][1] *= r1;
;                 }
;                 if (m == 1 || m == 3) __builtin_amdgcn_sched_barrier(0);
	v_lshlrev_b32_e32 v246, 16, v198
	v_and_b32_e32 v247, 0xffff0000, v198
	v_lshlrev_b32_e32 v248, 16, v199
	v_and_b32_e32 v249, 0xffff0000, v199
	v_max_f32_e32 v246, v246, v246
	v_max_f32_e32 v247, v247, v247
	v_max_f32_e32 v248, v248, v248
	v_max_f32_e32 v249, v249, v249
	v_max_f32_e32 v246, 0x1e3ce508, v246
	v_max_f32_e32 v247, 0x1e3ce508, v247
	v_max_f32_e32 v248, 0x1e3ce508, v248
	v_max_f32_e32 v249, 0x1e3ce508, v249
	v_rcp_f32_e32 v246, v246
	v_rcp_f32_e32 v247, v247
	v_rcp_f32_e32 v248, v248
	v_rcp_f32_e32 v249, v249
	v_lshlrev_b32_e32 v250, 16, v194
	v_and_b32_e32 v251, 0xffff0000, v194
	v_lshlrev_b32_e32 v252, 16, v195
	v_and_b32_e32 v253, 0xffff0000, v195
	v_pk_mul_f32 v[246:247], v[246:247], v[250:251]
	v_pk_mul_f32 v[248:249], v[248:249], v[252:253]
	v_pk_mul_f32 v[42:43], v[42:43], v[246:247]
	v_pk_mul_f32 v[44:45], v[44:45], v[248:249]
	v_lshlrev_b32_e32 v246, 16, v200
	v_and_b32_e32 v247, 0xffff0000, v200
	v_lshlrev_b32_e32 v248, 16, v201
	v_and_b32_e32 v249, 0xffff0000, v201
	v_max_f32_e32 v246, v246, v246
	v_max_f32_e32 v247, v247, v247
	v_max_f32_e32 v248, v248, v248
	v_max_f32_e32 v249, v249, v249
	v_max_f32_e32 v246, 0x1e3ce508, v246
	v_max_f32_e32 v247, 0x1e3ce508, v247
	v_max_f32_e32 v248, 0x1e3ce508, v248
	v_max_f32_e32 v249, 0x1e3ce508, v249
	v_rcp_f32_e32 v246, v246
	v_rcp_f32_e32 v247, v247
	v_rcp_f32_e32 v248, v248
	v_rcp_f32_e32 v249, v249
	v_lshlrev_b32_e32 v250, 16, v196
	v_and_b32_e32 v251, 0xffff0000, v196
	v_lshlrev_b32_e32 v252, 16, v197
	v_and_b32_e32 v253, 0xffff0000, v197
	v_pk_mul_f32 v[246:247], v[246:247], v[250:251]
	v_pk_mul_f32 v[248:249], v[248:249], v[252:253]
	v_pk_mul_f32 v[38:39], v[38:39], v[246:247]
	v_pk_mul_f32 v[40:41], v[40:41], v[248:249]
	s_waitcnt vmcnt(6)
	v_lshlrev_b32_e32 v246, 16, v206
	v_and_b32_e32 v247, 0xffff0000, v206
	v_lshlrev_b32_e32 v248, 16, v207
	v_and_b32_e32 v249, 0xffff0000, v207
	v_max_f32_e32 v246, v246, v246
	v_max_f32_e32 v247, v247, v247
	v_max_f32_e32 v248, v248, v248
	v_max_f32_e32 v249, v249, v249
	v_max_f32_e32 v246, 0x1e3ce508, v246
	v_max_f32_e32 v247, 0x1e3ce508, v247
	v_max_f32_e32 v248, 0x1e3ce508, v248
	v_max_f32_e32 v249, 0x1e3ce508, v249
	v_rcp_f32_e32 v246, v246
	v_rcp_f32_e32 v247, v247
	v_rcp_f32_e32 v248, v248
	v_rcp_f32_e32 v249, v249
	v_lshlrev_b32_e32 v250, 16, v202
	v_and_b32_e32 v251, 0xffff0000, v202
	v_lshlrev_b32_e32 v252, 16, v203
	v_and_b32_e32 v253, 0xffff0000, v203
	v_pk_mul_f32 v[246:247], v[246:247], v[250:251]
	v_pk_mul_f32 v[248:249], v[248:249], v[252:253]
	v_pk_mul_f32 v[28:29], v[28:29], v[246:247]
	v_pk_mul_f32 v[30:31], v[30:31], v[248:249]
	v_lshlrev_b32_e32 v246, 16, v208
	v_and_b32_e32 v247, 0xffff0000, v208
	v_lshlrev_b32_e32 v248, 16, v209
	v_and_b32_e32 v249, 0xffff0000, v209
	v_max_f32_e32 v246, v246, v246
	v_max_f32_e32 v247, v247, v247
	v_max_f32_e32 v248, v248, v248
	v_max_f32_e32 v249, v249, v249
	v_max_f32_e32 v246, 0x1e3ce508, v246
	v_max_f32_e32 v247, 0x1e3ce508, v247
	v_max_f32_e32 v248, 0x1e3ce508, v248
	v_max_f32_e32 v249, 0x1e3ce508, v249
	v_rcp_f32_e32 v246, v246
	v_rcp_f32_e32 v247, v247
	v_rcp_f32_e32 v248, v248
	v_rcp_f32_e32 v249, v249
	v_lshlrev_b32_e32 v250, 16, v204
	v_and_b32_e32 v251, 0xffff0000, v204
	v_lshlrev_b32_e32 v252, 16, v205
	v_and_b32_e32 v253, 0xffff0000, v205
	v_pk_mul_f32 v[246:247], v[246:247], v[250:251]
	v_pk_mul_f32 v[248:249], v[248:249], v[252:253]
	v_pk_mul_f32 v[24:25], v[24:25], v[246:247]
	v_pk_mul_f32 v[26:27], v[26:27], v[248:249]
	s_waitcnt vmcnt(4)
; __device__ __forceinline__ float fast_rcp(float x) { return __builtin_amdgcn_rcpf(x); }
;     __device__ __forceinline__ void mid(f32x4 (&acc)[2][2][4][2], const Unit& u, int wr, int wc, int fr, int fq, int t) const {
;     ...
;                     const u32x4 gn = *(const u32x4*)(gp + bj * 128), gd = *(const u32x4*)(gp + bj * 128 + 2048);
;                     f32x4 r0, r1;
;                     r0[0] = bflo(gn.x) * fast_rcp(fmaxf(bflo(gd.x), 1e-20f)); r0[1] = bfhi(gn.x) * fast_rcp(fmaxf(bfhi(gd.x), 1e-20f));
;                     r0[2] = bflo(gn.y) * fast_rcp(fmaxf(bflo(gd.y), 1e-20f)); r0[3] = bfhi(gn.y) * fast_rcp(fmaxf(bfhi(gd.y), 1e-20f));
;                     r1[0] = bflo(gn.z) * fast_rcp(fmaxf(bflo(gd.z), 1e-20f)); r1[1] = bfhi(gn.z) * fast_rcp(fmaxf(bfhi(gd.z), 1e-20f));
;                     r1[2] = bflo(gn.w) * fast_rcp(fmaxf(bflo(gd.w), 1e-20f)); r1[3] = bfhi(gn.w) * fast_rcp(fmaxf(bfhi(gd.w), 1e-20f));
;                     acc[ai][bj][m][0] *= r0; acc[ai][bj][m][1] *= r1;
;                 }
;                 if (m == 1 || m == 3) __builtin_amdgcn_sched_barrier(0);
	v_lshlrev_b32_e32 v246, 16, v214
	v_and_b32_e32 v247, 0xffff0000, v214
	v_lshlrev_b32_e32 v248, 16, v215
	v_and_b32_e32 v249, 0xffff0000, v215
	v_max_f32_e32 v246, v246, v246
	v_max_f32_e32 v247, v247, v247
	v_max_f32_e32 v248, v248, v248
	v_max_f32_e32 v249, v249, v249
	v_max_f32_e32 v246, 0x1e3ce508, v246
	v_max_f32_e32 v247, 0x1e3ce508, v247
	v_max_f32_e32 v248, 0x1e3ce508, v248
	v_max_f32_e32 v249, 0x1e3ce508, v249
	v_rcp_f32_e32 v246, v246
	v_rcp_f32_e32 v247, v247
	v_rcp_f32_e32 v248, v248
	v_rcp_f32_e32 v249, v249
	v_lshlrev_b32_e32 v250, 16, v210
	v_and_b32_e32 v251, 0xffff0000, v210
	v_lshlrev_b32_e32 v252, 16, v211
	v_and_b32_e32 v253, 0xffff0000, v211
	v_pk_mul_f32 v[246:247], v[246:247], v[250:251]
	v_pk_mul_f32 v[248:249], v[248:249], v[252:253]
	v_pk_mul_f32 v[20:21], v[20:21], v[246:247]
	v_pk_mul_f32 v[22:23], v[22:23], v[248:249]
	v_lshlrev_b32_e32 v246, 16, v216
	v_and_b32_e32 v247, 0xffff0000, v216
	v_lshlrev_b32_e32 v248, 16, v217
	v_and_b32_e32 v249, 0xffff0000, v217
	v_max_f32_e32 v246, v246, v246
	v_max_f32_e32 v247, v247, v247
	v_max_f32_e32 v248, v248, v248
	v_max_f32_e32 v249, v249, v249
	v_max_f32_e32 v246, 0x1e3ce508, v246
	v_max_f32_e32 v247, 0x1e3ce508, v247
	v_max_f32_e32 v248, 0x1e3ce508, v248
	v_max_f32_e32 v249, 0x1e3ce508, v249
	v_rcp_f32_e32 v246, v246
	v_rcp_f32_e32 v247, v247
	v_rcp_f32_e32 v248, v248
	v_rcp_f32_e32 v249, v249
	v_lshlrev_b32_e32 v250, 16, v212
	v_and_b32_e32 v251, 0xffff0000, v212
	v_lshlrev_b32_e32 v252, 16, v213
	v_and_b32_e32 v253, 0xffff0000, v213
	v_pk_mul_f32 v[246:247], v[246:247], v[250:251]
	v_pk_mul_f32 v[248:249], v[248:249], v[252:253]
	v_pk_mul_f32 v[16:17], v[16:17], v[246:247]
	v_pk_mul_f32 v[18:19], v[18:19], v[248:249]
	s_waitcnt vmcnt(2)
	v_lshlrev_b32_e32 v246, 16, v222
	v_and_b32_e32 v247, 0xffff0000, v222
	v_lshlrev_b32_e32 v248, 16, v223
	v_and_b32_e32 v249, 0xffff0000, v223
	v_max_f32_e32 v246, v246, v246
	v_max_f32_e32 v247, v247, v247
	v_max_f32_e32 v248, v248, v248
	v_max_f32_e32 v249, v249, v249
	v_max_f32_e32 v246, 0x1e3ce508, v246
	v_max_f32_e32 v247, 0x1e3ce508, v247
	v_max_f32_e32 v248, 0x1e3ce508, v248
	v_max_f32_e32 v249, 0x1e3ce508, v249
	v_rcp_f32_e32 v246, v246
	v_rcp_f32_e32 v247, v247
	v_rcp_f32_e32 v248, v248
	v_rcp_f32_e32 v249, v249
	v_lshlrev_b32_e32 v250, 16, v218
	v_and_b32_e32 v251, 0xffff0000, v218
	v_lshlrev_b32_e32 v252, 16, v219
	v_and_b32_e32 v253, 0xffff0000, v219
	v_pk_mul_f32 v[246:247], v[246:247], v[250:251]
	v_pk_mul_f32 v[248:249], v[248:249], v[252:253]
	v_pk_mul_f32 v[12:13], v[12:13], v[246:247]
	v_pk_mul_f32 v[14:15], v[14:15], v[248:249]
	v_lshlrev_b32_e32 v246, 16, v224
	v_and_b32_e32 v247, 0xffff0000, v224
	v_lshlrev_b32_e32 v248, 16, v225
	v_and_b32_e32 v249, 0xffff0000, v225
	v_max_f32_e32 v246, v246, v246
	v_max_f32_e32 v247, v247, v247
	v_max_f32_e32 v248, v248, v248
	v_max_f32_e32 v249, v249, v249
	v_max_f32_e32 v246, 0x1e3ce508, v246
	v_max_f32_e32 v247, 0x1e3ce508, v247
	v_max_f32_e32 v248, 0x1e3ce508, v248
	v_max_f32_e32 v249, 0x1e3ce508, v249
	v_rcp_f32_e32 v246, v246
	v_rcp_f32_e32 v247, v247
	v_rcp_f32_e32 v248, v248
	v_rcp_f32_e32 v249, v249
	v_lshlrev_b32_e32 v250, 16, v220
	v_and_b32_e32 v251, 0xffff0000, v220
	v_lshlrev_b32_e32 v252, 16, v221
	v_and_b32_e32 v253, 0xffff0000, v221
	v_pk_mul_f32 v[246:247], v[246:247], v[250:251]
	v_pk_mul_f32 v[248:249], v[248:249], v[252:253]
	v_pk_mul_f32 v[8:9], v[8:9], v[246:247]
	v_pk_mul_f32 v[10:11], v[10:11], v[248:249]
	s_waitcnt vmcnt(0)
	v_lshlrev_b32_e32 v246, 16, v230
	v_and_b32_e32 v247, 0xffff0000, v230
	v_lshlrev_b32_e32 v248, 16, v231
	v_and_b32_e32 v249, 0xffff0000, v231
	v_max_f32_e32 v246, v246, v246
	v_max_f32_e32 v247, v247, v247
	v_max_f32_e32 v248, v248, v248
	v_max_f32_e32 v249, v249, v249
	v_max_f32_e32 v246, 0x1e3ce508, v246
	v_max_f32_e32 v247, 0x1e3ce508, v247
	v_max_f32_e32 v248, 0x1e3ce508, v248
	v_max_f32_e32 v249, 0x1e3ce508, v249
	v_rcp_f32_e32 v246, v246
	v_rcp_f32_e32 v247, v247
	v_rcp_f32_e32 v248, v248
	v_rcp_f32_e32 v249, v249
	v_lshlrev_b32_e32 v250, 16, v226
	v_and_b32_e32 v251, 0xffff0000, v226
	v_lshlrev_b32_e32 v252, 16, v227
	v_and_b32_e32 v253, 0xffff0000, v227
	v_pk_mul_f32 v[246:247], v[246:247], v[250:251]
	v_pk_mul_f32 v[248:249], v[248:249], v[252:253]
	v_pk_mul_f32 v[4:5], v[4:5], v[246:247]
	v_pk_mul_f32 v[6:7], v[6:7], v[248:249]
	v_lshlrev_b32_e32 v246, 16, v232
	v_and_b32_e32 v247, 0xffff0000, v232
	v_lshlrev_b32_e32 v248, 16, v233
	v_and_b32_e32 v249, 0xffff0000, v233
	v_max_f32_e32 v246, v246, v246
	v_max_f32_e32 v247, v247, v247
	v_max_f32_e32 v248, v248, v248
	v_max_f32_e32 v249, v249, v249
	v_max_f32_e32 v246, 0x1e3ce508, v246
	v_max_f32_e32 v247, 0x1e3ce508, v247
	v_max_f32_e32 v248, 0x1e3ce508, v248
	v_max_f32_e32 v249, 0x1e3ce508, v249
	v_rcp_f32_e32 v246, v246
	v_rcp_f32_e32 v247, v247
	v_rcp_f32_e32 v248, v248
	v_rcp_f32_e32 v249, v249
	v_lshlrev_b32_e32 v250, 16, v228
	v_and_b32_e32 v251, 0xffff0000, v228
	v_lshlrev_b32_e32 v252, 16, v229
	v_and_b32_e32 v253, 0xffff0000, v229
	v_pk_mul_f32 v[246:247], v[246:247], v[250:251]
	v_pk_mul_f32 v[248:249], v[248:249], v[252:253]
	v_pk_mul_f32 v[0:1], v[0:1], v[246:247]
	v_pk_mul_f32 v[2:3], v[2:3], v[248:249]

; __device__ __forceinline__ unsigned pk2(float lo, float hi) { f32x2 v = {lo, hi}; bf16x2_t b = __builtin_convertvector(v, bf16x2_t); return __builtin_bit_cast(unsigned, b); }
;     __device__ __forceinline__ void operator()(const f32x4 (&acc)[2][2][4][2], const Unit& u, int wr, int wc, int fr, int fq) const {
;         const int row0 = u.pm * 256 + wr * 64 + fr, col0 = u.pn * 256 + wc * 32 + 8 * fq;
; #pragma unroll
;         for (int ai = 0; ai < 2; ++ai)
; #pragma unroll
;             for (int m = 0; m < 4; ++m) {
;                 const size_t row = (size_t)(row0 + ai * 128 + m * 16);
; #pragma unroll
;                 for (int bj = 0; bj < 2; ++bj) {
;                     const int col = col0 + bj * 128;
;                     const u32x4 g = *(const u32x4*)(P + row * PS + C_GATE + 4096 + col);
;                     f32x4 v0 = acc[ai][bj][m][0], v1 = acc[ai][bj][m][1];
;                     v0[0] *= fmaxf(bflo(g.x), 1e-20f); v0[1] *= fmaxf(bfhi(g.x), 1e-20f); v0[2] *= fmaxf(bflo(g.y), 1e-20f); v0[3] *= fmaxf(bfhi(g.y), 1e-20f);
;                     v1[0] *= fmaxf(bflo(g.z), 1e-20f); v1[1] *= fmaxf(bfhi(g.z), 1e-20f); v1[2] *= fmaxf(bflo(g.w), 1e-20f); v1[3] *= fmaxf(bfhi(g.w), 1e-20f);
;                     u32x4 w; w.x = pk2(v0[0], v0[1]); w.y = pk2(v0[2], v0[3]); w.z = pk2(v1[0], v1[1]); w.w = pk2(v1[2], v1[3]);
;                     *(u32x4*)(Yb + row * DM + col) = w;
.LBB0_795:
	v_lshl_add_u32 v34, s18, 8, v174
	v_mov_b64_e32 v[36:37], s[40:41]
	v_ashrrev_i32_e32 v159, 31, v158
	v_mad_i64_i32 v[36:37], vcc, v34, s90, v[36:37]
	v_lshlrev_b64 v[160:161], 1, v[158:159]
	v_lshl_add_u64 v[36:37], v[36:37], 0, s[36:37]
	v_mov_b32_e32 v164, v34
	v_ashrrev_i32_e32 v165, 31, v34
	v_lshl_add_u64 v[36:37], v[36:37], 0, v[160:161]
	v_lshlrev_b64 v[164:165], 12, v[164:165]
	v_lshl_add_u64 v[162:163], s[42:43], 0, v[164:165]
	v_lshl_add_u64 v[162:163], v[162:163], 0, v[160:161]
	s_mov_b32 s4, 0x60000
	s_mov_b32 s5, 0
	global_load_dwordx4 v[134:137], v[36:37], off
	global_load_dwordx4 v[138:141], v[36:37], off offset:256
	v_lshl_add_u64 v[36:37], v[36:37], 0, s[4:5]
	global_load_dwordx4 v[178:181], v[36:37], off
	global_load_dwordx4 v[182:185], v[36:37], off offset:256
	v_lshl_add_u64 v[36:37], v[36:37], 0, s[4:5]
	global_load_dwordx4 v[186:189], v[36:37], off
	global_load_dwordx4 v[190:193], v[36:37], off offset:256
	v_lshl_add_u64 v[36:37], v[36:37], 0, s[4:5]
	global_load_dwordx4 v[194:197], v[36:37], off
	global_load_dwordx4 v[198:201], v[36:37], off offset:256
	s_mov_b32 s4, 0x1e0000
	v_lshl_add_u64 v[36:37], v[36:37], 0, s[4:5]
	s_mov_b32 s4, 0x60000
	global_load_dwordx4 v[202:205], v[36:37], off
	global_load_dwordx4 v[206:209], v[36:37], off offset:256
	v_lshl_add_u64 v[36:37], v[36:37], 0, s[4:5]
	global_load_dwordx4 v[210:213], v[36:37], off
	global_load_dwordx4 v[214:217], v[36:37], off offset:256
	v_lshl_add_u64 v[36:37], v[36:37], 0, s[4:5]
	global_load_dwordx4 v[218:221], v[36:37], off
	global_load_dwordx4 v[222:225], v[36:37], off offset:256
	v_lshl_add_u64 v[36:37], v[36:37], 0, s[4:5]
	global_load_dwordx4 v[226:229], v[36:37], off
	global_load_dwordx4 v[230:233], v[36:37], off offset:256
	s_mov_b32 s4, 0x10000
	s_waitcnt vmcnt(15)
	v_lshlrev_b32_e32 v246, 16, v134
	v_and_b32_e32 v247, 0xffff0000, v134
	v_lshlrev_b32_e32 v248, 16, v135
	v_and_b32_e32 v249, 0xffff0000, v135
	v_max_f32_e32 v246, v246, v246
	v_max_f32_e32 v247, v247, v247
	v_max_f32_e32 v248, v248, v248
	v_max_f32_e32 v249, v249, v249
	v_max_f32_e32 v246, 0x1e3ce508, v246
	v_max_f32_e32 v247, 0x1e3ce508, v247
	v_max_f32_e32 v248, 0x1e3ce508, v248
	v_max_f32_e32 v249, 0x1e3ce508, v249
	v_pk_mul_f32 v[130:131], v[130:131], v[246:247]
	v_pk_mul_f32 v[132:133], v[132:133], v[248:249]
	v_lshlrev_b32_e32 v246, 16, v136
	v_and_b32_e32 v247, 0xffff0000, v136
	v_lshlrev_b32_e32 v248, 16, v137
	v_and_b32_e32 v249, 0xffff0000, v137
	v_max_f32_e32 v246, v246, v246
	v_max_f32_e32 v247, v247, v247
	v_max_f32_e32 v248, v248, v248
	v_max_f32_e32 v249, v249, v249
	v_max_f32_e32 v246, 0x1e3ce508, v246
	v_max_f32_e32 v247, 0x1e3ce508, v247
	v_max_f32_e32 v248, 0x1e3ce508, v248
	v_max_f32_e32 v249, 0x1e3ce508, v249
	v_pk_mul_f32 v[126:127], v[126:127], v[246:247]
	v_pk_mul_f32 v[128:129], v[128:129], v[248:249]
	v_cvt_pk_bf16_f32 v134, v130, v131
	v_cvt_pk_bf16_f32 v135, v132, v133
	v_cvt_pk_bf16_f32 v136, v126, v127
	v_cvt_pk_bf16_f32 v137, v128, v129
	global_store_dwordx4 v[162:163], v[134:137], off
	s_waitcnt vmcnt(15)
	v_lshlrev_b32_e32 v246, 16, v138
	v_and_b32_e32 v247, 0xffff0000, v138
	v_lshlrev_b32_e32 v248, 16, v139
	v_and_b32_e32 v249, 0xffff0000, v139
	v_max_f32_e32 v246, v246, v246
	v_max_f32_e32 v247, v247, v247
	v_max_f32_e32 v248, v248, v248
	v_max_f32_e32 v249, v249, v249
	v_max_f32_e32 v246, 0x1e3ce508, v246
	v_max_f32_e32 v247, 0x1e3ce508, v247
	v_max_f32_e32 v248, 0x1e3ce508, v248
	v_max_f32_e32 v249, 0x1e3ce508, v249
	v_pk_mul_f32 v[122:123], v[122:123], v[246:247]
	v_pk_mul_f32 v[124:125], v[124:125], v[248:249]
	v_lshlrev_b32_e32 v246, 16, v140
	v_and_b32_e32 v247, 0xffff0000, v140
	v_lshlrev_b32_e32 v248, 16, v141
	v_and_b32_e32 v249, 0xffff0000, v141
	v_max_f32_e32 v246, v246, v246
	v_max_f32_e32 v247, v247, v247
	v_max_f32_e32 v248, v248, v248
	v_max_f32_e32 v249, v249, v249
	v_max_f32_e32 v246, 0x1e3ce508, v246
	v_max_f32_e32 v247, 0x1e3ce508, v247
	v_max_f32_e32 v248, 0x1e3ce508, v248
	v_max_f32_e32 v249, 0x1e3ce508, v249
	v_pk_mul_f32 v[118:119], v[118:119], v[246:247]
	v_pk_mul_f32 v[120:121], v[120:121], v[248:249]
	v_cvt_pk_bf16_f32 v138, v122, v123
	v_cvt_pk_bf16_f32 v139, v124, v125
	v_cvt_pk_bf16_f32 v140, v118, v119
	v_cvt_pk_bf16_f32 v141, v120, v121
	global_store_dwordx4 v[162:163], v[138:141], off offset:256
	v_lshl_add_u64 v[162:163], v[162:163], 0, s[4:5]
	s_waitcnt vmcnt(15)
	v_lshlrev_b32_e32 v246, 16, v178
	v_and_b32_e32 v247, 0xffff0000, v178
	v_lshlrev_b32_e32 v248, 16, v179
	v_and_b32_e32 v249, 0xffff0000, v179
	v_max_f32_e32 v246, v246, v246
	v_max_f32_e32 v247, v247, v247
	v_max_f32_e32 v248, v248, v248
	v_max_f32_e32 v249, v249, v249
	v_max_f32_e32 v246, 0x1e3ce508, v246
	v_max_f32_e32 v247, 0x1e3ce508, v247
	v_max_f32_e32 v248, 0x1e3ce508, v248
	v_max_f32_e32 v249, 0x1e3ce508, v249
	v_pk_mul_f32 v[114:115], v[114:115], v[246:247]
	v_pk_mul_f32 v[116:117], v[116:117], v[248:249]
	v_lshlrev_b32_e32 v246, 16, v180
	v_and_b32_e32 v247, 0xffff0000, v180
	v_lshlrev_b32_e32 v248, 16, v181
	v_and_b32_e32 v249, 0xffff0000, v181
	v_max_f32_e32 v246, v246, v246
	v_max_f32_e32 v247, v247, v247
	v_max_f32_e32 v248, v248, v248
	v_max_f32_e32 v249, v249, v249
	v_max_f32_e32 v246, 0x1e3ce508, v246
	v_max_f32_e32 v247, 0x1e3ce508, v247
	v_max_f32_e32 v248, 0x1e3ce508, v248
	v_max_f32_e32 v249, 0x1e3ce508, v249
	v_pk_mul_f32 v[110:111], v[110:111], v[246:247]
	v_pk_mul_f32 v[112:113], v[112:113], v[248:249]
	v_cvt_pk_bf16_f32 v178, v114, v115
	v_cvt_pk_bf16_f32 v179, v116, v117
	v_cvt_pk_bf16_f32 v180, v110, v111
	v_cvt_pk_bf16_f32 v181, v112, v113
	global_store_dwordx4 v[162:163], v[178:181], off
	s_waitcnt vmcnt(15)
; __device__ __forceinline__ unsigned pk2(float lo, float hi) { f32x2 v = {lo, hi}; bf16x2_t b = __builtin_convertvector(v, bf16x2_t); return __builtin_bit_cast(unsigned, b); }
;     __device__ __forceinline__ void operator()(const f32x4 (&acc)[2][2][4][2], const Unit& u, int wr, int wc, int fr, int fq) const {
;     ...
;                 for (int bj = 0; bj < 2; ++bj) {
;                     const int col = col0 + bj * 128;
;                     const u32x4 g = *(const u32x4*)(P + row * PS + C_GATE + 4096 + col);
;                     f32x4 v0 = acc[ai][bj][m][0], v1 = acc[ai][bj][m][1];
;                     v0[0] *= fmaxf(bflo(g.x), 1e-20f); v0[1] *= fmaxf(bfhi(g.x), 1e-20f); v0[2] *= fmaxf(bflo(g.y), 1e-20f); v0[3] *= fmaxf(bfhi(g.y), 1e-20f);
;                     v1[0] *= fmaxf(bflo(g.z), 1e-20f); v1[1] *= fmaxf(bfhi(g.z), 1e-20f); v1[2] *= fmaxf(bflo(g.w), 1e-20f); v1[3] *= fmaxf(bfhi(g.w), 1e-20f);
;                     u32x4 w; w.x = pk2(v0[0], v0[1]); w.y = pk2(v0[2], v0[3]); w.z = pk2(v1[0], v1[1]); w.w = pk2(v1[2], v1[3]);
;                     *(u32x4*)(Yb + row * DM + col) = w;
	v_lshlrev_b32_e32 v246, 16, v182
	v_and_b32_e32 v247, 0xffff0000, v182
	v_lshlrev_b32_e32 v248, 16, v183
	v_and_b32_e32 v249, 0xffff0000, v183
	v_max_f32_e32 v246, v246, v246
	v_max_f32_e32 v247, v247, v247
	v_max_f32_e32 v248, v248, v248
	v_max_f32_e32 v249, v249, v249
	v_max_f32_e32 v246, 0x1e3ce508, v246
	v_max_f32_e32 v247, 0x1e3ce508, v247
	v_max_f32_e32 v248, 0x1e3ce508, v248
	v_max_f32_e32 v249, 0x1e3ce508, v249
	v_pk_mul_f32 v[106:107], v[106:107], v[246:247]
	v_pk_mul_f32 v[108:109], v[108:109], v[248:249]
	v_lshlrev_b32_e32 v246, 16, v184
	v_and_b32_e32 v247, 0xffff0000, v184
	v_lshlrev_b32_e32 v248, 16, v185
	v_and_b32_e32 v249, 0xffff0000, v185
	v_max_f32_e32 v246, v246, v246
	v_max_f32_e32 v247, v247, v247
	v_max_f32_e32 v248, v248, v248
	v_max_f32_e32 v249, v249, v249
	v_max_f32_e32 v246, 0x1e3ce508, v246
	v_max_f32_e32 v247, 0x1e3ce508, v247
	v_max_f32_e32 v248, 0x1e3ce508, v248
	v_max_f32_e32 v249, 0x1e3ce508, v249
	v_pk_mul_f32 v[102:103], v[102:103], v[246:247]
	v_pk_mul_f32 v[104:105], v[104:105], v[248:249]
	v_cvt_pk_bf16_f32 v182, v106, v107
	v_cvt_pk_bf16_f32 v183, v108, v109
	v_cvt_pk_bf16_f32 v184, v102, v103
	v_cvt_pk_bf16_f32 v185, v104, v105
	global_store_dwordx4 v[162:163], v[182:185], off offset:256
	v_lshl_add_u64 v[162:163], v[162:163], 0, s[4:5]
	s_waitcnt vmcnt(15)
	v_lshlrev_b32_e32 v246, 16, v186
	v_and_b32_e32 v247, 0xffff0000, v186
	v_lshlrev_b32_e32 v248, 16, v187
	v_and_b32_e32 v249, 0xffff0000, v187
	v_max_f32_e32 v246, v246, v246
	v_max_f32_e32 v247, v247, v247
	v_max_f32_e32 v248, v248, v248
	v_max_f32_e32 v249, v249, v249
	v_max_f32_e32 v246, 0x1e3ce508, v246
	v_max_f32_e32 v247, 0x1e3ce508, v247
	v_max_f32_e32 v248, 0x1e3ce508, v248
	v_max_f32_e32 v249, 0x1e3ce508, v249
	v_pk_mul_f32 v[98:99], v[98:99], v[246:247]
	v_pk_mul_f32 v[100:101], v[100:101], v[248:249]
	v_lshlrev_b32_e32 v246, 16, v188
	v_and_b32_e32 v247, 0xffff0000, v188
	v_lshlrev_b32_e32 v248, 16, v189
	v_and_b32_e32 v249, 0xffff0000, v189
	v_max_f32_e32 v246, v246, v246
	v_max_f32_e32 v247, v247, v247
	v_max_f32_e32 v248, v248, v248
	v_max_f32_e32 v249, v249, v249
	v_max_f32_e32 v246, 0x1e3ce508, v246
	v_max_f32_e32 v247, 0x1e3ce508, v247
	v_max_f32_e32 v248, 0x1e3ce508, v248
	v_max_f32_e32 v249, 0x1e3ce508, v249
	v_pk_mul_f32 v[94:95], v[94:95], v[246:247]
	v_pk_mul_f32 v[96:97], v[96:97], v[248:249]
	v_cvt_pk_bf16_f32 v186, v98, v99
	v_cvt_pk_bf16_f32 v187, v100, v101
	v_cvt_pk_bf16_f32 v188, v94, v95
	v_cvt_pk_bf16_f32 v189, v96, v97
	global_store_dwordx4 v[162:163], v[186:189], off
	s_waitcnt vmcnt(15)
	v_lshlrev_b32_e32 v246, 16, v190
	v_and_b32_e32 v247, 0xffff0000, v190
	v_lshlrev_b32_e32 v248, 16, v191
	v_and_b32_e32 v249, 0xffff0000, v191
	v_max_f32_e32 v246, v246, v246
	v_max_f32_e32 v247, v247, v247
	v_max_f32_e32 v248, v248, v248
	v_max_f32_e32 v249, v249, v249
	v_max_f32_e32 v246, 0x1e3ce508, v246
	v_max_f32_e32 v247, 0x1e3ce508, v247
	v_max_f32_e32 v248, 0x1e3ce508, v248
	v_max_f32_e32 v249, 0x1e3ce508, v249
	v_pk_mul_f32 v[90:91], v[90:91], v[246:247]
	v_pk_mul_f32 v[92:93], v[92:93], v[248:249]
	v_lshlrev_b32_e32 v246, 16, v192
	v_and_b32_e32 v247, 0xffff0000, v192
	v_lshlrev_b32_e32 v248, 16, v193
	v_and_b32_e32 v249, 0xffff0000, v193
	v_max_f32_e32 v246, v246, v246
	v_max_f32_e32 v247, v247, v247
	v_max_f32_e32 v248, v248, v248
	v_max_f32_e32 v249, v249, v249
	v_max_f32_e32 v246, 0x1e3ce508, v246
	v_max_f32_e32 v247, 0x1e3ce508, v247
	v_max_f32_e32 v248, 0x1e3ce508, v248
	v_max_f32_e32 v249, 0x1e3ce508, v249
	v_pk_mul_f32 v[86:87], v[86:87], v[246:247]
	v_pk_mul_f32 v[88:89], v[88:89], v[248:249]
	v_cvt_pk_bf16_f32 v190, v90, v91
	v_cvt_pk_bf16_f32 v191, v92, v93
	v_cvt_pk_bf16_f32 v192, v86, v87
	v_cvt_pk_bf16_f32 v193, v88, v89
	global_store_dwordx4 v[162:163], v[190:193], off offset:256
	v_lshl_add_u64 v[162:163], v[162:163], 0, s[4:5]
	s_waitcnt vmcnt(15)
	v_lshlrev_b32_e32 v246, 16, v194
	v_and_b32_e32 v247, 0xffff0000, v194
	v_lshlrev_b32_e32 v248, 16, v195
	v_and_b32_e32 v249, 0xffff0000, v195
	v_max_f32_e32 v246, v246, v246
	v_max_f32_e32 v247, v247, v247
	v_max_f32_e32 v248, v248, v248
	v_max_f32_e32 v249, v249, v249
	v_max_f32_e32 v246, 0x1e3ce508, v246
	v_max_f32_e32 v247, 0x1e3ce508, v247
	v_max_f32_e32 v248, 0x1e3ce508, v248
	v_max_f32_e32 v249, 0x1e3ce508, v249
	v_pk_mul_f32 v[82:83], v[82:83], v[246:247]
	v_pk_mul_f32 v[84:85], v[84:85], v[248:249]
	v_lshlrev_b32_e32 v246, 16, v196
	v_and_b32_e32 v247, 0xffff0000, v196
	v_lshlrev_b32_e32 v248, 16, v197
	v_and_b32_e32 v249, 0xffff0000, v197
	v_max_f32_e32 v246, v246, v246
	v_max_f32_e32 v247, v247, v247
	v_max_f32_e32 v248, v248, v248
	v_max_f32_e32 v249, v249, v249
	v_max_f32_e32 v246, 0x1e3ce508, v246
	v_max_f32_e32 v247, 0x1e3ce508, v247
	v_max_f32_e32 v248, 0x1e3ce508, v248
	v_max_f32_e32 v249, 0x1e3ce508, v249
	v_pk_mul_f32 v[78:79], v[78:79], v[246:247]
	v_pk_mul_f32 v[80:81], v[80:81], v[248:249]
	v_cvt_pk_bf16_f32 v194, v82, v83
	v_cvt_pk_bf16_f32 v195, v84, v85
	v_cvt_pk_bf16_f32 v196, v78, v79
	v_cvt_pk_bf16_f32 v197, v80, v81
	global_store_dwordx4 v[162:163], v[194:197], off
	s_waitcnt vmcnt(15)
; __device__ __forceinline__ unsigned pk2(float lo, float hi) { f32x2 v = {lo, hi}; bf16x2_t b = __builtin_convertvector(v, bf16x2_t); return __builtin_bit_cast(unsigned, b); }
;     __device__ __forceinline__ void operator()(const f32x4 (&acc)[2][2][4][2], const Unit& u, int wr, int wc, int fr, int fq) const {
;     ...
;                 for (int bj = 0; bj < 2; ++bj) {
;                     const int col = col0 + bj * 128;
;                     const u32x4 g = *(const u32x4*)(P + row * PS + C_GATE + 4096 + col);
;                     f32x4 v0 = acc[ai][bj][m][0], v1 = acc[ai][bj][m][1];
;                     v0[0] *= fmaxf(bflo(g.x), 1e-20f); v0[1] *= fmaxf(bfhi(g.x), 1e-20f); v0[2] *= fmaxf(bflo(g.y), 1e-20f); v0[3] *= fmaxf(bfhi(g.y), 1e-20f);
;                     v1[0] *= fmaxf(bflo(g.z), 1e-20f); v1[1] *= fmaxf(bfhi(g.z), 1e-20f); v1[2] *= fmaxf(bflo(g.w), 1e-20f); v1[3] *= fmaxf(bfhi(g.w), 1e-20f);
;                     u32x4 w; w.x = pk2(v0[0], v0[1]); w.y = pk2(v0[2], v0[3]); w.z = pk2(v1[0], v1[1]); w.w = pk2(v1[2], v1[3]);
;                     *(u32x4*)(Yb + row * DM + col) = w;
	v_lshlrev_b32_e32 v246, 16, v198
	v_and_b32_e32 v247, 0xffff0000, v198
	v_lshlrev_b32_e32 v248, 16, v199
	v_and_b32_e32 v249, 0xffff0000, v199
	v_max_f32_e32 v246, v246, v246
	v_max_f32_e32 v247, v247, v247
	v_max_f32_e32 v248, v248, v248
	v_max_f32_e32 v249, v249, v249
	v_max_f32_e32 v246, 0x1e3ce508, v246
	v_max_f32_e32 v247, 0x1e3ce508, v247
	v_max_f32_e32 v248, 0x1e3ce508, v248
	v_max_f32_e32 v249, 0x1e3ce508, v249
	v_pk_mul_f32 v[74:75], v[74:75], v[246:247]
	v_pk_mul_f32 v[76:77], v[76:77], v[248:249]
	v_lshlrev_b32_e32 v246, 16, v200
	v_and_b32_e32 v247, 0xffff0000, v200
	v_lshlrev_b32_e32 v248, 16, v201
	v_and_b32_e32 v249, 0xffff0000, v201
	v_max_f32_e32 v246, v246, v246
	v_max_f32_e32 v247, v247, v247
	v_max_f32_e32 v248, v248, v248
	v_max_f32_e32 v249, v249, v249
	v_max_f32_e32 v246, 0x1e3ce508, v246
	v_max_f32_e32 v247, 0x1e3ce508, v247
	v_max_f32_e32 v248, 0x1e3ce508, v248
	v_max_f32_e32 v249, 0x1e3ce508, v249
	v_pk_mul_f32 v[70:71], v[70:71], v[246:247]
	v_pk_mul_f32 v[72:73], v[72:73], v[248:249]
	v_cvt_pk_bf16_f32 v198, v74, v75
	v_cvt_pk_bf16_f32 v199, v76, v77
	v_cvt_pk_bf16_f32 v200, v70, v71
	v_cvt_pk_bf16_f32 v201, v72, v73
	global_store_dwordx4 v[162:163], v[198:201], off offset:256
	s_mov_b32 s4, 0x50000
	v_lshl_add_u64 v[162:163], v[162:163], 0, s[4:5]
	s_mov_b32 s4, 0x10000
	s_waitcnt vmcnt(15)
	v_lshlrev_b32_e32 v246, 16, v202
	v_and_b32_e32 v247, 0xffff0000, v202
	v_lshlrev_b32_e32 v248, 16, v203
	v_and_b32_e32 v249, 0xffff0000, v203
	v_max_f32_e32 v246, v246, v246
	v_max_f32_e32 v247, v247, v247
	v_max_f32_e32 v248, v248, v248
	v_max_f32_e32 v249, v249, v249
	v_max_f32_e32 v246, 0x1e3ce508, v246
	v_max_f32_e32 v247, 0x1e3ce508, v247
	v_max_f32_e32 v248, 0x1e3ce508, v248
	v_max_f32_e32 v249, 0x1e3ce508, v249
	v_pk_mul_f32 v[66:67], v[66:67], v[246:247]
	v_pk_mul_f32 v[68:69], v[68:69], v[248:249]
	v_lshlrev_b32_e32 v246, 16, v204
	v_and_b32_e32 v247, 0xffff0000, v204
	v_lshlrev_b32_e32 v248, 16, v205
	v_and_b32_e32 v249, 0xffff0000, v205
	v_max_f32_e32 v246, v246, v246
	v_max_f32_e32 v247, v247, v247
	v_max_f32_e32 v248, v248, v248
	v_max_f32_e32 v249, v249, v249
	v_max_f32_e32 v246, 0x1e3ce508, v246
	v_max_f32_e32 v247, 0x1e3ce508, v247
	v_max_f32_e32 v248, 0x1e3ce508, v248
	v_max_f32_e32 v249, 0x1e3ce508, v249
	v_pk_mul_f32 v[62:63], v[62:63], v[246:247]
	v_pk_mul_f32 v[64:65], v[64:65], v[248:249]
	v_cvt_pk_bf16_f32 v202, v66, v67
	v_cvt_pk_bf16_f32 v203, v68, v69
	v_cvt_pk_bf16_f32 v204, v62, v63
	v_cvt_pk_bf16_f32 v205, v64, v65
	global_store_dwordx4 v[162:163], v[202:205], off
	s_waitcnt vmcnt(15)
	v_lshlrev_b32_e32 v246, 16, v206
	v_and_b32_e32 v247, 0xffff0000, v206
	v_lshlrev_b32_e32 v248, 16, v207
	v_and_b32_e32 v249, 0xffff0000, v207
	v_max_f32_e32 v246, v246, v246
	v_max_f32_e32 v247, v247, v247
	v_max_f32_e32 v248, v248, v248
	v_max_f32_e32 v249, v249, v249
	v_max_f32_e32 v246, 0x1e3ce508, v246
	v_max_f32_e32 v247, 0x1e3ce508, v247
	v_max_f32_e32 v248, 0x1e3ce508, v248
	v_max_f32_e32 v249, 0x1e3ce508, v249
	v_pk_mul_f32 v[58:59], v[58:59], v[246:247]
	v_pk_mul_f32 v[60:61], v[60:61], v[248:249]
	v_lshlrev_b32_e32 v246, 16, v208
	v_and_b32_e32 v247, 0xffff0000, v208
	v_lshlrev_b32_e32 v248, 16, v209
	v_and_b32_e32 v249, 0xffff0000, v209
	v_max_f32_e32 v246, v246, v246
	v_max_f32_e32 v247, v247, v247
	v_max_f32_e32 v248, v248, v248
	v_max_f32_e32 v249, v249, v249
	v_max_f32_e32 v246, 0x1e3ce508, v246
	v_max_f32_e32 v247, 0x1e3ce508, v247
	v_max_f32_e32 v248, 0x1e3ce508, v248
	v_max_f32_e32 v249, 0x1e3ce508, v249
	v_pk_mul_f32 v[54:55], v[54:55], v[246:247]
	v_pk_mul_f32 v[56:57], v[56:57], v[248:249]
	v_cvt_pk_bf16_f32 v206, v58, v59
	v_cvt_pk_bf16_f32 v207, v60, v61
	v_cvt_pk_bf16_f32 v208, v54, v55
	v_cvt_pk_bf16_f32 v209, v56, v57
	global_store_dwordx4 v[162:163], v[206:209], off offset:256
	v_lshl_add_u64 v[162:163], v[162:163], 0, s[4:5]
	s_waitcnt vmcnt(15)
	v_lshlrev_b32_e32 v246, 16, v210
	v_and_b32_e32 v247, 0xffff0000, v210
	v_lshlrev_b32_e32 v248, 16, v211
	v_and_b32_e32 v249, 0xffff0000, v211
	v_max_f32_e32 v246, v246, v246
	v_max_f32_e32 v247, v247, v247
	v_max_f32_e32 v248, v248, v248
	v_max_f32_e32 v249, v249, v249
	v_max_f32_e32 v246, 0x1e3ce508, v246
	v_max_f32_e32 v247, 0x1e3ce508, v247
	v_max_f32_e32 v248, 0x1e3ce508, v248
	v_max_f32_e32 v249, 0x1e3ce508, v249
	v_pk_mul_f32 v[50:51], v[50:51], v[246:247]
	v_pk_mul_f32 v[52:53], v[52:53], v[248:249]
	v_lshlrev_b32_e32 v246, 16, v212
	v_and_b32_e32 v247, 0xffff0000, v212
	v_lshlrev_b32_e32 v248, 16, v213
	v_and_b32_e32 v249, 0xffff0000, v213
	v_max_f32_e32 v246, v246, v246
	v_max_f32_e32 v247, v247, v247
	v_max_f32_e32 v248, v248, v248
	v_max_f32_e32 v249, v249, v249
	v_max_f32_e32 v246, 0x1e3ce508, v246
	v_max_f32_e32 v247, 0x1e3ce508, v247
	v_max_f32_e32 v248, 0x1e3ce508, v248
	v_max_f32_e32 v249, 0x1e3ce508, v249
	v_pk_mul_f32 v[46:47], v[46:47], v[246:247]
	v_pk_mul_f32 v[48:49], v[48:49], v[248:249]
	v_cvt_pk_bf16_f32 v210, v50, v51
	v_cvt_pk_bf16_f32 v211, v52, v53
	v_cvt_pk_bf16_f32 v212, v46, v47
	v_cvt_pk_bf16_f32 v213, v48, v49
	global_store_dwordx4 v[162:163], v[210:213], off
	s_waitcnt vmcnt(15)
; #define PG8_BAR __builtin_amdgcn_s_barrier()
; __device__ __forceinline__ unsigned pk2(float lo, float hi) { f32x2 v = {lo, hi}; bf16x2_t b = __builtin_convertvector(v, bf16x2_t); return __builtin_bit_cast(unsigned, b); }
; template <class Epi, class Sched, bool ALIGN_EPI = false, bool SP2 = false>
; __device__ __forceinline__ void gemm_phase(PG8_LAS unsigned char* lds, const Gemm g, const Sched& S, const Epi& E) {
;     ...
;         if (!has_next) break;
; #pragma unroll
;         for (int a = 0; a < 2; ++a)
; #pragma unroll
;             for (int b = 0; b < 2; ++b)
; #pragma unroll
;                 for (int m = 0; m < 4; ++m)
; #pragma unroll
;                     for (int n = 0; n < 2; ++n) acc[a][b][m][n] = (f32x4){0.f, 0.f, 0.f, 0.f};
;         cur = nxt; cA = nA; cB = nB; ++ui;
;         if constexpr (ALIGN_EPI) { if (wr == 1) PG8_BAR; }
;     __device__ __forceinline__ void operator()(const f32x4 (&acc)[2][2][4][2], const Unit& u, int wr, int wc, int fr, int fq) const {
;     ...
;                 for (int bj = 0; bj < 2; ++bj) {
;                     const int col = col0 + bj * 128;
;                     const u32x4 g = *(const u32x4*)(P + row * PS + C_GATE + 4096 + col);
;                     f32x4 v0 = acc[ai][bj][m][0], v1 = acc[ai][bj][m][1];
;                     v0[0] *= fmaxf(bflo(g.x), 1e-20f); v0[1] *= fmaxf(bfhi(g.x), 1e-20f); v0[2] *= fmaxf(bflo(g.y), 1e-20f); v0[3] *= fmaxf(bfhi(g.y), 1e-20f);
;                     v1[0] *= fmaxf(bflo(g.z), 1e-20f); v1[1] *= fmaxf(bfhi(g.z), 1e-20f); v1[2] *= fmaxf(bflo(g.w), 1e-20f); v1[3] *= fmaxf(bfhi(g.w), 1e-20f);
;                     u32x4 w; w.x = pk2(v0[0], v0[1]); w.y = pk2(v0[2], v0[3]); w.z = pk2(v1[0], v1[1]); w.w = pk2(v1[2], v1[3]);
;                     *(u32x4*)(Yb + row * DM + col) = w;
	v_lshlrev_b32_e32 v246, 16, v214
	v_and_b32_e32 v247, 0xffff0000, v214
	v_lshlrev_b32_e32 v248, 16, v215
	v_and_b32_e32 v249, 0xffff0000, v215
	v_max_f32_e32 v246, v246, v246
	v_max_f32_e32 v247, v247, v247
	v_max_f32_e32 v248, v248, v248
	v_max_f32_e32 v249, v249, v249
	v_max_f32_e32 v246, 0x1e3ce508, v246
	v_max_f32_e32 v247, 0x1e3ce508, v247
	v_max_f32_e32 v248, 0x1e3ce508, v248
	v_max_f32_e32 v249, 0x1e3ce508, v249
	v_pk_mul_f32 v[42:43], v[42:43], v[246:247]
	v_pk_mul_f32 v[44:45], v[44:45], v[248:249]
	v_lshlrev_b32_e32 v246, 16, v216
	v_and_b32_e32 v247, 0xffff0000, v216
	v_lshlrev_b32_e32 v248, 16, v217
	v_and_b32_e32 v249, 0xffff0000, v217
	v_max_f32_e32 v246, v246, v246
	v_max_f32_e32 v247, v247, v247
	v_max_f32_e32 v248, v248, v248
	v_max_f32_e32 v249, v249, v249
	v_max_f32_e32 v246, 0x1e3ce508, v246
	v_max_f32_e32 v247, 0x1e3ce508, v247
	v_max_f32_e32 v248, 0x1e3ce508, v248
	v_max_f32_e32 v249, 0x1e3ce508, v249
	v_pk_mul_f32 v[38:39], v[38:39], v[246:247]
	v_pk_mul_f32 v[40:41], v[40:41], v[248:249]
	v_cvt_pk_bf16_f32 v214, v42, v43
	v_cvt_pk_bf16_f32 v215, v44, v45
	v_cvt_pk_bf16_f32 v216, v38, v39
	v_cvt_pk_bf16_f32 v217, v40, v41
	global_store_dwordx4 v[162:163], v[214:217], off offset:256
	v_lshl_add_u64 v[162:163], v[162:163], 0, s[4:5]
	s_waitcnt vmcnt(15)
	v_lshlrev_b32_e32 v246, 16, v218
	v_and_b32_e32 v247, 0xffff0000, v218
	v_lshlrev_b32_e32 v248, 16, v219
	v_and_b32_e32 v249, 0xffff0000, v219
	v_max_f32_e32 v246, v246, v246
	v_max_f32_e32 v247, v247, v247
	v_max_f32_e32 v248, v248, v248
	v_max_f32_e32 v249, v249, v249
	v_max_f32_e32 v246, 0x1e3ce508, v246
	v_max_f32_e32 v247, 0x1e3ce508, v247
	v_max_f32_e32 v248, 0x1e3ce508, v248
	v_max_f32_e32 v249, 0x1e3ce508, v249
	v_pk_mul_f32 v[28:29], v[28:29], v[246:247]
	v_pk_mul_f32 v[30:31], v[30:31], v[248:249]
	v_lshlrev_b32_e32 v246, 16, v220
	v_and_b32_e32 v247, 0xffff0000, v220
	v_lshlrev_b32_e32 v248, 16, v221
	v_and_b32_e32 v249, 0xffff0000, v221
	v_max_f32_e32 v246, v246, v246
	v_max_f32_e32 v247, v247, v247
	v_max_f32_e32 v248, v248, v248
	v_max_f32_e32 v249, v249, v249
	v_max_f32_e32 v246, 0x1e3ce508, v246
	v_max_f32_e32 v247, 0x1e3ce508, v247
	v_max_f32_e32 v248, 0x1e3ce508, v248
	v_max_f32_e32 v249, 0x1e3ce508, v249
	v_pk_mul_f32 v[24:25], v[24:25], v[246:247]
	v_pk_mul_f32 v[26:27], v[26:27], v[248:249]
	v_cvt_pk_bf16_f32 v218, v28, v29
	v_cvt_pk_bf16_f32 v219, v30, v31
	v_cvt_pk_bf16_f32 v220, v24, v25
	v_cvt_pk_bf16_f32 v221, v26, v27
	global_store_dwordx4 v[162:163], v[218:221], off
	s_waitcnt vmcnt(15)
	v_lshlrev_b32_e32 v246, 16, v222
	v_and_b32_e32 v247, 0xffff0000, v222
	v_lshlrev_b32_e32 v248, 16, v223
	v_and_b32_e32 v249, 0xffff0000, v223
	v_max_f32_e32 v246, v246, v246
	v_max_f32_e32 v247, v247, v247
	v_max_f32_e32 v248, v248, v248
	v_max_f32_e32 v249, v249, v249
	v_max_f32_e32 v246, 0x1e3ce508, v246
	v_max_f32_e32 v247, 0x1e3ce508, v247
	v_max_f32_e32 v248, 0x1e3ce508, v248
	v_max_f32_e32 v249, 0x1e3ce508, v249
	v_pk_mul_f32 v[20:21], v[20:21], v[246:247]
	v_pk_mul_f32 v[22:23], v[22:23], v[248:249]
	v_lshlrev_b32_e32 v246, 16, v224
	v_and_b32_e32 v247, 0xffff0000, v224
	v_lshlrev_b32_e32 v248, 16, v225
	v_and_b32_e32 v249, 0xffff0000, v225
	v_max_f32_e32 v246, v246, v246
	v_max_f32_e32 v247, v247, v247
	v_max_f32_e32 v248, v248, v248
	v_max_f32_e32 v249, v249, v249
	v_max_f32_e32 v246, 0x1e3ce508, v246
	v_max_f32_e32 v247, 0x1e3ce508, v247
	v_max_f32_e32 v248, 0x1e3ce508, v248
	v_max_f32_e32 v249, 0x1e3ce508, v249
	v_pk_mul_f32 v[16:17], v[16:17], v[246:247]
	v_pk_mul_f32 v[18:19], v[18:19], v[248:249]
	v_cvt_pk_bf16_f32 v222, v20, v21
	v_cvt_pk_bf16_f32 v223, v22, v23
	v_cvt_pk_bf16_f32 v224, v16, v17
	v_cvt_pk_bf16_f32 v225, v18, v19
	global_store_dwordx4 v[162:163], v[222:225], off offset:256
	v_lshl_add_u64 v[162:163], v[162:163], 0, s[4:5]
	s_waitcnt vmcnt(15)
	v_lshlrev_b32_e32 v246, 16, v226
	v_and_b32_e32 v247, 0xffff0000, v226
	v_lshlrev_b32_e32 v248, 16, v227
	v_and_b32_e32 v249, 0xffff0000, v227
	v_max_f32_e32 v246, v246, v246
	v_max_f32_e32 v247, v247, v247
	v_max_f32_e32 v248, v248, v248
	v_max_f32_e32 v249, v249, v249
	v_max_f32_e32 v246, 0x1e3ce508, v246
	v_max_f32_e32 v247, 0x1e3ce508, v247
	v_max_f32_e32 v248, 0x1e3ce508, v248
	v_max_f32_e32 v249, 0x1e3ce508, v249
	v_pk_mul_f32 v[12:13], v[12:13], v[246:247]
	v_pk_mul_f32 v[14:15], v[14:15], v[248:249]
	v_lshlrev_b32_e32 v246, 16, v228
	v_and_b32_e32 v247, 0xffff0000, v228
	v_lshlrev_b32_e32 v248, 16, v229
	v_and_b32_e32 v249, 0xffff0000, v229
	v_max_f32_e32 v246, v246, v246
	v_max_f32_e32 v247, v247, v247
	v_max_f32_e32 v248, v248, v248
	v_max_f32_e32 v249, v249, v249
	v_max_f32_e32 v246, 0x1e3ce508, v246
	v_max_f32_e32 v247, 0x1e3ce508, v247
	v_max_f32_e32 v248, 0x1e3ce508, v248
	v_max_f32_e32 v249, 0x1e3ce508, v249
	v_pk_mul_f32 v[8:9], v[8:9], v[246:247]
	v_pk_mul_f32 v[10:11], v[10:11], v[248:249]
	v_cvt_pk_bf16_f32 v226, v12, v13
	v_cvt_pk_bf16_f32 v227, v14, v15
	v_cvt_pk_bf16_f32 v228, v8, v9
	v_cvt_pk_bf16_f32 v229, v10, v11
	global_store_dwordx4 v[162:163], v[226:229], off
	s_waitcnt vmcnt(15)
	v_lshlrev_b32_e32 v246, 16, v230
	v_and_b32_e32 v247, 0xffff0000, v230
	v_lshlrev_b32_e32 v248, 16, v231
	v_and_b32_e32 v249, 0xffff0000, v231
	v_max_f32_e32 v246, v246, v246
	v_max_f32_e32 v247, v247, v247
	v_max_f32_e32 v248, v248, v248
	v_max_f32_e32 v249, v249, v249
	v_max_f32_e32 v246, 0x1e3ce508, v246
	v_max_f32_e32 v247, 0x1e3ce508, v247
	v_max_f32_e32 v248, 0x1e3ce508, v248
	v_max_f32_e32 v249, 0x1e3ce508, v249
	v_pk_mul_f32 v[4:5], v[4:5], v[246:247]
	v_pk_mul_f32 v[6:7], v[6:7], v[248:249]
	v_lshlrev_b32_e32 v246, 16, v232
	v_and_b32_e32 v247, 0xffff0000, v232
	v_lshlrev_b32_e32 v248, 16, v233
	v_and_b32_e32 v249, 0xffff0000, v233
	v_max_f32_e32 v246, v246, v246
	v_max_f32_e32 v247, v247, v247
	v_max_f32_e32 v248, v248, v248
	v_max_f32_e32 v249, v249, v249
	v_max_f32_e32 v246, 0x1e3ce508, v246
	v_max_f32_e32 v247, 0x1e3ce508, v247
	v_max_f32_e32 v248, 0x1e3ce508, v248
	v_max_f32_e32 v249, 0x1e3ce508, v249
	v_pk_mul_f32 v[0:1], v[0:1], v[246:247]
	v_pk_mul_f32 v[2:3], v[2:3], v[248:249]
	v_cvt_pk_bf16_f32 v230, v4, v5
	v_cvt_pk_bf16_f32 v231, v6, v7
	v_cvt_pk_bf16_f32 v232, v0, v1
	v_cvt_pk_bf16_f32 v233, v2, v3
	global_store_dwordx4 v[162:163], v[230:233], off offset:256
	s_andn2_b64 vcc, exec, s[56:57]
	s_mov_b64 s[0:1], -1
	s_cbranch_vccnz .LBB0_776
	s_andn2_b64 vcc, exec, s[38:39]
	s_cbranch_vccnz .LBB0_775
	s_barrier
	s_branch .LBB0_775
